# gMLP LayerNorm statistics: 2 coalesced loads per wave + 8-lane DPP sum + exchange through LDS pad bytes (was 16 lane-strided loads per wave, 64 cache lines per instruction)
# speedup vs baseline: 1.0123x; 1.0044x over previous
.LBB0_124:
	s_ashr_i32 s14, s16, 9
	s_ashr_i32 s15, s14, 31
	s_lshl_b64 s[14:15], s[14:15], 12
	s_and_b32 s19, s18, 0xf80
	s_or_b32 s14, s14, s19
	v_mov_b32_e32 v1, s15
	v_or_b32_e32 v0, s14, v156
	s_and_b32 s20, s17, 0x3c0
	v_lshlrev_b64 v[2:3], 7, v[0:1]
	v_lshlrev_b64 v[0:1], 11, v[0:1]
	v_lshl_add_u64 v[0:1], s[28:29], 0, v[0:1]
	s_lshl_b32 s78, s20, 1
	v_lshl_add_u64 v[2:3], s[0:1], 0, v[2:3]
	v_lshl_add_u64 v[28:29], v[0:1], 0, s[78:79]
	s_lshl_b32 s100, s83, 4
	v_lshrrev_b32_e32 v76, 3, v244
	v_add_u32_e32 v76, s100, v76
	s_add_i32 s100, s100, s14
	s_lshl_b32 s100, s100, 7
	s_add_u32 s100, s0, s100
	s_addc_u32 s101, s1, 0
	v_lshlrev_b32_e32 v60, 4, v244
	global_load_dwordx4 v[56:59], v60, s[100:101]
	global_load_dwordx4 v[64:67], v60, s[100:101] offset:1024
	global_load_dwordx4 v[32:35], v[28:29], off offset:48
	global_load_dwordx4 v[40:43], v[28:29], off offset:32
	global_load_dwordx4 v[48:51], v[28:29], off offset:16
	global_load_dwordx4 v[120:123], v[28:29], off
	global_load_dwordx4 v[36:39], v[28:29], off offset:2096
	global_load_dwordx4 v[44:47], v[28:29], off offset:2080
	global_load_dwordx4 v[52:55], v[28:29], off offset:2064
	global_load_dwordx4 v[124:127], v[28:29], off offset:2048
	global_load_dwordx4 v[0:3], v[28:29], off offset:112
	global_load_dwordx4 v[8:11], v[28:29], off offset:96
	global_load_dwordx4 v[16:19], v[28:29], off offset:80
	global_load_dwordx4 v[24:27], v[28:29], off offset:64
	global_load_dwordx4 v[4:7], v[28:29], off offset:2160
	global_load_dwordx4 v[12:15], v[28:29], off offset:2144
	global_load_dwordx4 v[20:23], v[28:29], off offset:2128
	s_nop 0
	global_load_dwordx4 v[28:31], v[28:29], off offset:2112
	s_lshl_b32 s22, s20, 2
	s_add_i32 s22, s22, 0
	s_add_i32 s24, s22, 0x22000
	s_add_i32 s22, s22, 0x23000
	s_and_b32 s19, s17, 0x380
	v_add_u32_e32 v175, v165, v169
	v_mov_b32_e32 v155, s15
	v_or_b32_e32 v154, s14, v164
	v_add_u32_e32 v177, v165, v171
	v_mov_b32_e32 v151, s15
	v_or_b32_e32 v150, s14, v166
	v_mov_b32_e32 v147, s15
	v_or_b32_e32 v146, s14, v168
	v_mov_b32_e32 v145, s15
	v_or_b32_e32 v144, s14, v176
	s_add_i32 s16, s16, s26
	s_add_i32 s17, s17, s55
	s_add_i32 s18, s18, s23
	s_cmpk_lt_i32 s16, 0x800
	s_waitcnt vmcnt(16)
	s_nop 0
	v_add_f32_e32 v60, v56, v58
	v_add_f32_e32 v61, v57, v59
	v_add_f32_e32 v68, v64, v66
	v_add_f32_e32 v69, v65, v67
	v_add_f32_dpp v60, v60, v60 quad_perm:[1,0,3,2] row_mask:0xf bank_mask:0xf
	v_add_f32_dpp v61, v61, v61 quad_perm:[1,0,3,2] row_mask:0xf bank_mask:0xf
	v_add_f32_dpp v68, v68, v68 quad_perm:[1,0,3,2] row_mask:0xf bank_mask:0xf
	v_add_f32_dpp v69, v69, v69 quad_perm:[1,0,3,2] row_mask:0xf bank_mask:0xf
	v_add_f32_dpp v60, v60, v60 quad_perm:[2,3,0,1] row_mask:0xf bank_mask:0xf
	v_add_f32_dpp v61, v61, v61 quad_perm:[2,3,0,1] row_mask:0xf bank_mask:0xf
	v_add_f32_dpp v68, v68, v68 quad_perm:[2,3,0,1] row_mask:0xf bank_mask:0xf
	v_add_f32_dpp v69, v69, v69 quad_perm:[2,3,0,1] row_mask:0xf bank_mask:0xf
	v_add_f32_dpp v60, v60, v60 row_half_mirror row_mask:0xf bank_mask:0xf
	v_add_f32_dpp v61, v61, v61 row_half_mirror row_mask:0xf bank_mask:0xf
	v_add_f32_dpp v68, v68, v68 row_half_mirror row_mask:0xf bank_mask:0xf
	v_add_f32_dpp v69, v69, v69 row_half_mirror row_mask:0xf bank_mask:0xf
	s_nop 1
	v_mov_b32_e32 v128, v61
	v_mul_f32_e32 v129, s44, v60
	s_nop 0
	v_mov_b32_e32 v195, v129
	v_pk_mul_f32 v[58:59], v[128:129], v[194:195]
	s_nop 0
	v_sub_f32_e32 v58, v58, v59
	v_max_f32_e32 v58, 0, v58
	v_add_f32_e32 v58, 0x358637bd, v58
	v_cmp_gt_f32_e32 vcc, s61, v58
	v_mul_f32_e32 v59, 0x4f800000, v58
	s_nop 0
	v_cndmask_b32_e32 v58, v58, v59, vcc
	v_sqrt_f32_e32 v59, v58
	s_nop 0
	v_add_u32_e32 v71, -1, v59
	v_fma_f32 v72, -v71, v59, v58
	v_cmp_ge_f32_e64 s[70:71], 0, v72
	v_add_u32_e32 v72, 1, v59
	s_nop 0
	v_cndmask_b32_e64 v71, v59, v71, s[70:71]
	v_fma_f32 v59, -v72, v59, v58
	v_cmp_lt_f32_e64 s[70:71], 0, v59
	s_nop 1
	v_cndmask_b32_e64 v59, v71, v72, s[70:71]
	v_mul_f32_e32 v71, 0x37800000, v59
	v_cndmask_b32_e32 v59, v59, v71, vcc
	v_cmp_class_f32_e32 vcc, v58, v226
	s_nop 1
	v_cndmask_b32_e32 v58, v59, v58, vcc
	v_div_scale_f32 v59, s[70:71], v58, v58, 1.0
	v_rcp_f32_e32 v71, v59
	s_nop 0
	v_fma_f32 v72, -v59, v71, 1.0
	v_fmac_f32_e32 v71, v72, v71
	v_div_scale_f32 v72, vcc, 1.0, v58, 1.0
	v_mul_f32_e32 v73, v72, v71
	v_fma_f32 v74, -v59, v73, v72
	v_fmac_f32_e32 v73, v74, v71
	v_fma_f32 v59, -v59, v73, v72
	v_div_fmas_f32 v59, v59, v71, v73
	v_div_fixup_f32 v59, v59, v58, 1.0
	v_mov_b32_e32 v61, v59
	v_mov_b32_e32 v128, v69
	v_mul_f32_e32 v129, s44, v68
	s_nop 0
	v_mov_b32_e32 v195, v129
	v_pk_mul_f32 v[58:59], v[128:129], v[194:195]
	s_nop 0
	v_sub_f32_e32 v58, v58, v59
	v_max_f32_e32 v58, 0, v58
	v_add_f32_e32 v58, 0x358637bd, v58
	v_cmp_gt_f32_e32 vcc, s61, v58
	v_mul_f32_e32 v59, 0x4f800000, v58
	s_nop 0
	v_cndmask_b32_e32 v58, v58, v59, vcc
	v_sqrt_f32_e32 v59, v58
	s_nop 0
	v_add_u32_e32 v71, -1, v59
	v_fma_f32 v72, -v71, v59, v58
	v_cmp_ge_f32_e64 s[70:71], 0, v72
	v_add_u32_e32 v72, 1, v59
	s_nop 0
	v_cndmask_b32_e64 v71, v59, v71, s[70:71]
	v_fma_f32 v59, -v72, v59, v58
	v_cmp_lt_f32_e64 s[70:71], 0, v59
	s_nop 1
	v_cndmask_b32_e64 v59, v71, v72, s[70:71]
	v_mul_f32_e32 v71, 0x37800000, v59
	v_cndmask_b32_e32 v59, v59, v71, vcc
	v_cmp_class_f32_e32 vcc, v58, v226
	s_nop 1
	v_cndmask_b32_e32 v58, v59, v58, vcc
	v_div_scale_f32 v59, s[70:71], v58, v58, 1.0
	v_rcp_f32_e32 v71, v59
	s_nop 0
	v_fma_f32 v72, -v59, v71, 1.0
	v_fmac_f32_e32 v71, v72, v71
	v_div_scale_f32 v72, vcc, 1.0, v58, 1.0
	v_mul_f32_e32 v73, v72, v71
	v_fma_f32 v74, -v59, v73, v72
	v_fmac_f32_e32 v73, v74, v71
	v_fma_f32 v59, -v59, v73, v72
	v_div_fmas_f32 v59, v59, v71, v73
	v_div_fixup_f32 v59, v59, v58, 1.0
	v_mov_b32_e32 v69, v59
	v_lshrrev_b32_e32 v77, 1, v76
	v_and_b32_e32 v78, 1, v76
	v_mul_u32_u24_e32 v77, 0x110, v77
	v_lshl_add_u32 v77, v78, 3, v77
	ds_write_b64 v77, v[60:61] offset:256
	ds_write_b64 v77, v[68:69] offset:1344
	v_mul_u32_u24_e32 v77, 0x110, v244
	s_waitcnt lgkmcnt(0)
	s_barrier
	ds_read_b128 v[100:103], v77 offset:256
	s_waitcnt lgkmcnt(0)
	v_mov_b32_e32 v56, v100
	v_mov_b32_e32 v58, v101
	v_mov_b32_e32 v57, v102
	v_mov_b32_e32 v59, v103
	v_mov_b32_e32 v60, s24
	v_mov_b32_e32 v61, s22
	s_waitcnt vmcnt(0)
	ds_read_b128 v[62:65], v60
	ds_read_b128 v[66:69], v60 offset:16
	ds_read_b128 v[92:95], v61
	ds_read_b128 v[96:99], v61 offset:16
	v_lshlrev_b32_e32 v79, 16, v52
	v_lshlrev_b32_e32 v78, 16, v48
	v_and_b32_e32 v81, 0xffff0000, v52
	v_and_b32_e32 v80, 0xffff0000, v48
	v_pk_fma_f32 v[78:79], v[56:57], s[44:45], v[78:79] op_sel_hi:[1,0,1] neg_lo:[1,0,0] neg_hi:[1,0,0]
	v_pk_fma_f32 v[80:81], v[56:57], s[44:45], v[80:81] op_sel_hi:[1,0,1] neg_lo:[1,0,0] neg_hi:[1,0,0]
	v_lshlrev_b32_e32 v71, 16, v124
	v_lshlrev_b32_e32 v70, 16, v120
	v_and_b32_e32 v73, 0xffff0000, v124
	v_and_b32_e32 v72, 0xffff0000, v120
	v_pk_fma_f32 v[70:71], v[56:57], s[44:45], v[70:71] op_sel_hi:[1,0,1] neg_lo:[1,0,0] neg_hi:[1,0,0]
	v_pk_fma_f32 v[72:73], v[56:57], s[44:45], v[72:73] op_sel_hi:[1,0,1] neg_lo:[1,0,0] neg_hi:[1,0,0]
	v_pk_mul_f32 v[70:71], v[70:71], v[58:59]
	v_pk_mul_f32 v[72:73], v[72:73], v[58:59]
	s_waitcnt lgkmcnt(1)
	v_pk_fma_f32 v[70:71], v[62:63], v[70:71], v[92:93] op_sel_hi:[0,1,0]
	v_pk_fma_f32 v[62:63], v[62:63], v[72:73], v[92:93] op_sel:[1,0,1]
	v_cvt_pk_bf16_f32 v70, v70, v71
	v_cvt_pk_bf16_f32 v62, v62, v63
	ds_write2_b32 v161, v70, v62 offset1:68
	v_lshlrev_b32_e32 v63, 16, v125
	v_lshlrev_b32_e32 v62, 16, v121
	v_pk_fma_f32 v[62:63], v[56:57], s[44:45], v[62:63] op_sel_hi:[1,0,1] neg_lo:[1,0,0] neg_hi:[1,0,0]
	v_and_b32_e32 v71, 0xffff0000, v125
	v_and_b32_e32 v70, 0xffff0000, v121
	v_pk_mul_f32 v[62:63], v[62:63], v[58:59]
	v_pk_fma_f32 v[70:71], v[56:57], s[44:45], v[70:71] op_sel_hi:[1,0,1] neg_lo:[1,0,0] neg_hi:[1,0,0]
	v_pk_fma_f32 v[62:63], v[64:65], v[62:63], v[94:95] op_sel_hi:[0,1,0]
	v_pk_mul_f32 v[70:71], v[70:71], v[58:59]
	v_mov_b32_e32 v64, v65
	v_mov_b32_e32 v72, v95
	v_pk_fma_f32 v[64:65], v[64:65], v[70:71], v[72:73] op_sel_hi:[0,1,0]
	v_cvt_pk_bf16_f32 v62, v62, v63
	v_cvt_pk_bf16_f32 v63, v64, v65
	ds_write2_b32 v161, v62, v63 offset0:136 offset1:204
	v_lshlrev_b32_e32 v63, 16, v126
	v_lshlrev_b32_e32 v62, 16, v122
	v_and_b32_e32 v65, 0xffff0000, v126
	v_and_b32_e32 v64, 0xffff0000, v122
	v_pk_fma_f32 v[62:63], v[56:57], s[44:45], v[62:63] op_sel_hi:[1,0,1] neg_lo:[1,0,0] neg_hi:[1,0,0]
	v_pk_fma_f32 v[64:65], v[56:57], s[44:45], v[64:65] op_sel_hi:[1,0,1] neg_lo:[1,0,0] neg_hi:[1,0,0]
	v_pk_mul_f32 v[62:63], v[62:63], v[58:59]
	v_pk_mul_f32 v[64:65], v[64:65], v[58:59]
	s_waitcnt lgkmcnt(2)
	v_pk_fma_f32 v[62:63], v[66:67], v[62:63], v[96:97] op_sel_hi:[0,1,0]
	v_pk_fma_f32 v[64:65], v[66:67], v[64:65], v[96:97] op_sel:[1,0,1]
	v_cvt_pk_bf16_f32 v62, v62, v63
	v_cvt_pk_bf16_f32 v63, v64, v65
	v_add_u32_e32 v67, 0x800, v161
	ds_write2_b32 v67, v62, v63 offset0:32 offset1:100
	v_lshlrev_b32_e32 v63, 16, v127
	v_lshlrev_b32_e32 v62, 16, v123
	v_pk_fma_f32 v[62:63], v[56:57], s[44:45], v[62:63] op_sel_hi:[1,0,1] neg_lo:[1,0,0] neg_hi:[1,0,0]
	v_and_b32_e32 v65, 0xffff0000, v127
	v_and_b32_e32 v64, 0xffff0000, v123
	v_pk_mul_f32 v[62:63], v[62:63], v[58:59]
	v_pk_fma_f32 v[64:65], v[56:57], s[44:45], v[64:65] op_sel_hi:[1,0,1] neg_lo:[1,0,0] neg_hi:[1,0,0]
	v_pk_fma_f32 v[62:63], v[68:69], v[62:63], v[98:99] op_sel_hi:[0,1,0]
	v_pk_mul_f32 v[64:65], v[64:65], v[58:59]
	v_mov_b32_e32 v66, v69
	v_mov_b32_e32 v68, v99
	v_pk_fma_f32 v[64:65], v[66:67], v[64:65], v[68:69] op_sel_hi:[0,1,0]
	v_cvt_pk_bf16_f32 v62, v62, v63
	v_cvt_pk_bf16_f32 v63, v64, v65
	ds_write2_b32 v67, v62, v63 offset0:168 offset1:236
	ds_read_b128 v[62:65], v60 offset:32
	ds_read_b128 v[66:69], v60 offset:48
	ds_read_b128 v[70:73], v61 offset:32
	ds_read_b128 v[74:77], v61 offset:48
	v_pk_mul_f32 v[78:79], v[78:79], v[58:59]
	v_pk_mul_f32 v[80:81], v[80:81], v[58:59]
	s_waitcnt lgkmcnt(1)
	v_pk_fma_f32 v[78:79], v[62:63], v[78:79], v[70:71] op_sel_hi:[0,1,0]
	v_pk_fma_f32 v[62:63], v[62:63], v[80:81], v[70:71] op_sel:[1,0,1]
	v_cvt_pk_bf16_f32 v48, v78, v79
	v_cvt_pk_bf16_f32 v52, v62, v63
	v_add_u32_e32 v62, 0x1000, v161
	ds_write2_b32 v62, v48, v52 offset0:64 offset1:132
	v_lshlrev_b32_e32 v63, 16, v53
	v_lshlrev_b32_e32 v62, 16, v49
	v_pk_fma_f32 v[62:63], v[56:57], s[44:45], v[62:63] op_sel_hi:[1,0,1] neg_lo:[1,0,0] neg_hi:[1,0,0]
	v_and_b32_e32 v53, 0xffff0000, v53
	v_and_b32_e32 v52, 0xffff0000, v49
	v_pk_mul_f32 v[62:63], v[62:63], v[58:59]
	v_pk_fma_f32 v[48:49], v[56:57], s[44:45], v[52:53] op_sel_hi:[1,0,1] neg_lo:[1,0,0] neg_hi:[1,0,0]
	v_pk_fma_f32 v[62:63], v[64:65], v[62:63], v[72:73] op_sel_hi:[0,1,0]
	v_pk_mul_f32 v[48:49], v[48:49], v[58:59]
	v_mov_b32_e32 v52, v65
	v_mov_b32_e32 v64, v73
	v_pk_fma_f32 v[48:49], v[52:53], v[48:49], v[64:65] op_sel_hi:[0,1,0]
	v_cvt_pk_bf16_f32 v52, v62, v63
	v_cvt_pk_bf16_f32 v48, v48, v49
	v_add_u32_e32 v49, 0x1200, v161
	ds_write2_b32 v49, v52, v48 offset0:72 offset1:140
	v_lshlrev_b32_e32 v49, 16, v54
	v_lshlrev_b32_e32 v48, 16, v50
	v_and_b32_e32 v53, 0xffff0000, v54
	v_and_b32_e32 v52, 0xffff0000, v50
	v_pk_fma_f32 v[48:49], v[56:57], s[44:45], v[48:49] op_sel_hi:[1,0,1] neg_lo:[1,0,0] neg_hi:[1,0,0]
	v_pk_fma_f32 v[52:53], v[56:57], s[44:45], v[52:53] op_sel_hi:[1,0,1] neg_lo:[1,0,0] neg_hi:[1,0,0]
	v_pk_mul_f32 v[48:49], v[48:49], v[58:59]
	v_pk_mul_f32 v[52:53], v[52:53], v[58:59]
	s_waitcnt lgkmcnt(2)
	v_pk_fma_f32 v[48:49], v[66:67], v[48:49], v[74:75] op_sel_hi:[0,1,0]
	v_pk_fma_f32 v[52:53], v[66:67], v[52:53], v[74:75] op_sel:[1,0,1]
	v_cvt_pk_bf16_f32 v48, v48, v49
	v_cvt_pk_bf16_f32 v49, v52, v53
	v_add_u32_e32 v50, 0x1800, v161
	ds_write2_b32 v50, v48, v49 offset0:96 offset1:164
	v_lshlrev_b32_e32 v49, 16, v55
	v_lshlrev_b32_e32 v48, 16, v51
	v_and_b32_e32 v53, 0xffff0000, v55
	v_and_b32_e32 v52, 0xffff0000, v51
	v_pk_fma_f32 v[48:49], v[56:57], s[44:45], v[48:49] op_sel_hi:[1,0,1] neg_lo:[1,0,0] neg_hi:[1,0,0]
	v_pk_fma_f32 v[50:51], v[56:57], s[44:45], v[52:53] op_sel_hi:[1,0,1] neg_lo:[1,0,0] neg_hi:[1,0,0]
	v_pk_mul_f32 v[48:49], v[48:49], v[58:59]
	v_pk_mul_f32 v[50:51], v[50:51], v[58:59]
	v_mov_b32_e32 v52, v69
	v_mov_b32_e32 v54, v77
	v_pk_fma_f32 v[48:49], v[68:69], v[48:49], v[76:77] op_sel_hi:[0,1,0]
	v_pk_fma_f32 v[50:51], v[52:53], v[50:51], v[54:55] op_sel_hi:[0,1,0]
	v_cvt_pk_bf16_f32 v48, v48, v49
	v_cvt_pk_bf16_f32 v49, v50, v51
	v_add_u32_e32 v50, 0x1a00, v161
	ds_write2_b32 v50, v48, v49 offset0:104 offset1:172
	ds_read_b128 v[48:51], v60 offset:64
	ds_read_b128 v[52:55], v60 offset:80
	ds_read_b128 v[62:65], v61 offset:64
	ds_read_b128 v[66:69], v61 offset:80
	v_lshlrev_b32_e32 v71, 16, v44
	v_lshlrev_b32_e32 v70, 16, v40
	v_and_b32_e32 v73, 0xffff0000, v44
	v_and_b32_e32 v72, 0xffff0000, v40
	v_pk_fma_f32 v[70:71], v[56:57], s[44:45], v[70:71] op_sel_hi:[1,0,1] neg_lo:[1,0,0] neg_hi:[1,0,0]
	v_pk_fma_f32 v[72:73], v[56:57], s[44:45], v[72:73] op_sel_hi:[1,0,1] neg_lo:[1,0,0] neg_hi:[1,0,0]
	v_pk_mul_f32 v[70:71], v[70:71], v[58:59]
	v_pk_mul_f32 v[72:73], v[72:73], v[58:59]
	s_waitcnt lgkmcnt(1)
	v_pk_fma_f32 v[70:71], v[70:71], v[48:49], v[62:63] op_sel_hi:[1,0,0]
	v_pk_fma_f32 v[48:49], v[72:73], v[48:49], v[62:63] op_sel:[0,1,1]
	v_cvt_pk_bf16_f32 v40, v70, v71
	v_cvt_pk_bf16_f32 v44, v48, v49
	v_add_u32_e32 v62, 0x400, v161
	v_lshlrev_b32_e32 v49, 16, v45
	v_lshlrev_b32_e32 v48, 16, v41
	ds_write2_b32 v62, v40, v44 offset0:16 offset1:84
	v_pk_fma_f32 v[48:49], v[56:57], s[44:45], v[48:49] op_sel_hi:[1,0,1] neg_lo:[1,0,0] neg_hi:[1,0,0]
	v_and_b32_e32 v45, 0xffff0000, v45
	v_and_b32_e32 v44, 0xffff0000, v41
	v_pk_mul_f32 v[48:49], v[48:49], v[58:59]
	v_pk_fma_f32 v[40:41], v[56:57], s[44:45], v[44:45] op_sel_hi:[1,0,1] neg_lo:[1,0,0] neg_hi:[1,0,0]
	v_pk_fma_f32 v[48:49], v[48:49], v[50:51], v[64:65] op_sel_hi:[1,0,0]
	v_pk_mul_f32 v[40:41], v[40:41], v[58:59]
	v_mov_b32_e32 v44, v51
	v_mov_b32_e32 v50, v65
	v_pk_fma_f32 v[40:41], v[40:41], v[44:45], v[50:51] op_sel_hi:[1,0,0]
	v_cvt_pk_bf16_f32 v44, v48, v49
	v_cvt_pk_bf16_f32 v40, v40, v41
	ds_write2_b32 v62, v44, v40 offset0:152 offset1:220
	v_lshlrev_b32_e32 v41, 16, v46
	v_lshlrev_b32_e32 v40, 16, v42
	v_and_b32_e32 v45, 0xffff0000, v46
	v_and_b32_e32 v44, 0xffff0000, v42
	v_pk_fma_f32 v[40:41], v[56:57], s[44:45], v[40:41] op_sel_hi:[1,0,1] neg_lo:[1,0,0] neg_hi:[1,0,0]
	v_pk_fma_f32 v[44:45], v[56:57], s[44:45], v[44:45] op_sel_hi:[1,0,1] neg_lo:[1,0,0] neg_hi:[1,0,0]
	v_pk_mul_f32 v[40:41], v[40:41], v[58:59]
	v_pk_mul_f32 v[44:45], v[44:45], v[58:59]
	s_waitcnt lgkmcnt(2)
	v_pk_fma_f32 v[40:41], v[40:41], v[52:53], v[66:67] op_sel_hi:[1,0,0]
	v_pk_fma_f32 v[44:45], v[44:45], v[52:53], v[66:67] op_sel:[0,1,1]
	v_cvt_pk_bf16_f32 v40, v40, v41
	v_cvt_pk_bf16_f32 v41, v44, v45
	v_add_u32_e32 v48, 0xc00, v161
	ds_write2_b32 v48, v40, v41 offset0:48 offset1:116
	v_lshlrev_b32_e32 v41, 16, v47
	v_lshlrev_b32_e32 v40, 16, v43
	v_and_b32_e32 v45, 0xffff0000, v47
	v_and_b32_e32 v44, 0xffff0000, v43
	v_pk_fma_f32 v[40:41], v[56:57], s[44:45], v[40:41] op_sel_hi:[1,0,1] neg_lo:[1,0,0] neg_hi:[1,0,0]
	v_pk_fma_f32 v[42:43], v[56:57], s[44:45], v[44:45] op_sel_hi:[1,0,1] neg_lo:[1,0,0] neg_hi:[1,0,0]
	v_pk_mul_f32 v[40:41], v[40:41], v[58:59]
	v_pk_mul_f32 v[42:43], v[42:43], v[58:59]
	v_mov_b32_e32 v44, v55
	v_mov_b32_e32 v46, v69
	v_pk_fma_f32 v[40:41], v[40:41], v[54:55], v[68:69] op_sel_hi:[1,0,0]
	v_pk_fma_f32 v[42:43], v[42:43], v[44:45], v[46:47] op_sel_hi:[1,0,0]
	v_cvt_pk_bf16_f32 v40, v40, v41
	v_cvt_pk_bf16_f32 v41, v42, v43
	ds_write2_b32 v48, v40, v41 offset0:184 offset1:252
	ds_read_b128 v[40:43], v60 offset:96
	ds_read_b128 v[44:47], v60 offset:112
	ds_read_b128 v[48:51], v61 offset:96
	ds_read_b128 v[52:55], v61 offset:112
	v_lshlrev_b32_e32 v63, 16, v36
	v_lshlrev_b32_e32 v62, 16, v32
	v_and_b32_e32 v65, 0xffff0000, v36
	v_and_b32_e32 v64, 0xffff0000, v32
	v_pk_fma_f32 v[62:63], v[56:57], s[44:45], v[62:63] op_sel_hi:[1,0,1] neg_lo:[1,0,0] neg_hi:[1,0,0]
	v_pk_fma_f32 v[64:65], v[56:57], s[44:45], v[64:65] op_sel_hi:[1,0,1] neg_lo:[1,0,0] neg_hi:[1,0,0]
	v_pk_mul_f32 v[62:63], v[62:63], v[58:59]
	v_pk_mul_f32 v[64:65], v[64:65], v[58:59]
	s_waitcnt lgkmcnt(1)
	v_pk_fma_f32 v[62:63], v[62:63], v[40:41], v[48:49] op_sel_hi:[1,0,0]
	v_pk_fma_f32 v[40:41], v[64:65], v[40:41], v[48:49] op_sel:[0,1,1]
	v_cvt_pk_bf16_f32 v32, v62, v63
	v_cvt_pk_bf16_f32 v36, v40, v41
	v_add_u32_e32 v40, 0x1400, v161
	ds_write2_b32 v40, v32, v36 offset0:80 offset1:148
	v_lshlrev_b32_e32 v41, 16, v37
	v_lshlrev_b32_e32 v40, 16, v33
	v_pk_fma_f32 v[40:41], v[56:57], s[44:45], v[40:41] op_sel_hi:[1,0,1] neg_lo:[1,0,0] neg_hi:[1,0,0]
	v_and_b32_e32 v37, 0xffff0000, v37
	v_and_b32_e32 v36, 0xffff0000, v33
	v_pk_mul_f32 v[40:41], v[40:41], v[58:59]
	v_pk_fma_f32 v[32:33], v[56:57], s[44:45], v[36:37] op_sel_hi:[1,0,1] neg_lo:[1,0,0] neg_hi:[1,0,0]
	v_pk_fma_f32 v[40:41], v[40:41], v[42:43], v[50:51] op_sel_hi:[1,0,0]
	v_pk_mul_f32 v[32:33], v[32:33], v[58:59]
	v_mov_b32_e32 v36, v43
	v_mov_b32_e32 v42, v51
	v_pk_fma_f32 v[32:33], v[32:33], v[36:37], v[42:43] op_sel_hi:[1,0,0]
	v_cvt_pk_bf16_f32 v36, v40, v41
	v_cvt_pk_bf16_f32 v32, v32, v33
	v_add_u32_e32 v33, 0x1600, v161
	ds_write2_b32 v33, v36, v32 offset0:88 offset1:156
	v_lshlrev_b32_e32 v33, 16, v38
	v_lshlrev_b32_e32 v32, 16, v34
	v_and_b32_e32 v37, 0xffff0000, v38
	v_and_b32_e32 v36, 0xffff0000, v34
	v_pk_fma_f32 v[32:33], v[56:57], s[44:45], v[32:33] op_sel_hi:[1,0,1] neg_lo:[1,0,0] neg_hi:[1,0,0]
	v_pk_fma_f32 v[36:37], v[56:57], s[44:45], v[36:37] op_sel_hi:[1,0,1] neg_lo:[1,0,0] neg_hi:[1,0,0]
	v_pk_mul_f32 v[32:33], v[32:33], v[58:59]
	v_pk_mul_f32 v[36:37], v[36:37], v[58:59]
	s_waitcnt lgkmcnt(2)
	v_pk_fma_f32 v[32:33], v[32:33], v[44:45], v[52:53] op_sel_hi:[1,0,0]
	v_pk_fma_f32 v[36:37], v[36:37], v[44:45], v[52:53] op_sel:[0,1,1]
	v_cvt_pk_bf16_f32 v32, v32, v33
	v_cvt_pk_bf16_f32 v33, v36, v37
	v_add_u32_e32 v34, 0x1c00, v161
	ds_write2_b32 v34, v32, v33 offset0:112 offset1:180
	v_lshlrev_b32_e32 v33, 16, v39
	v_lshlrev_b32_e32 v32, 16, v35
	v_and_b32_e32 v37, 0xffff0000, v39
	v_and_b32_e32 v36, 0xffff0000, v35
	v_pk_fma_f32 v[32:33], v[56:57], s[44:45], v[32:33] op_sel_hi:[1,0,1] neg_lo:[1,0,0] neg_hi:[1,0,0]
	v_pk_fma_f32 v[34:35], v[56:57], s[44:45], v[36:37] op_sel_hi:[1,0,1] neg_lo:[1,0,0] neg_hi:[1,0,0]
	v_pk_mul_f32 v[32:33], v[32:33], v[58:59]
	v_pk_mul_f32 v[34:35], v[34:35], v[58:59]
	v_mov_b32_e32 v36, v47
	v_mov_b32_e32 v38, v55
	v_pk_fma_f32 v[32:33], v[32:33], v[46:47], v[54:55] op_sel_hi:[1,0,0]
	v_pk_fma_f32 v[34:35], v[34:35], v[36:37], v[38:39] op_sel_hi:[1,0,0]
	v_cvt_pk_bf16_f32 v32, v32, v33
	v_cvt_pk_bf16_f32 v33, v34, v35
	v_add_u32_e32 v34, 0x1e00, v161
	ds_write2_b32 v34, v32, v33 offset0:120 offset1:188
	ds_read_b128 v[32:35], v60 offset:128
	ds_read_b128 v[36:39], v60 offset:144
	ds_read_b128 v[40:43], v61 offset:128
	ds_read_b128 v[44:47], v61 offset:144
	v_lshlrev_b32_e32 v49, 16, v28
	v_lshlrev_b32_e32 v48, 16, v24
	v_and_b32_e32 v51, 0xffff0000, v28
	v_and_b32_e32 v50, 0xffff0000, v24
	v_pk_fma_f32 v[48:49], v[56:57], s[44:45], v[48:49] op_sel_hi:[1,0,1] neg_lo:[1,0,0] neg_hi:[1,0,0]
	v_pk_fma_f32 v[50:51], v[56:57], s[44:45], v[50:51] op_sel_hi:[1,0,1] neg_lo:[1,0,0] neg_hi:[1,0,0]
	v_pk_mul_f32 v[48:49], v[48:49], v[58:59]
	v_pk_mul_f32 v[50:51], v[50:51], v[58:59]
	s_waitcnt lgkmcnt(1)
	v_pk_fma_f32 v[48:49], v[48:49], v[32:33], v[40:41] op_sel_hi:[1,0,0]
	v_pk_fma_f32 v[32:33], v[50:51], v[32:33], v[40:41] op_sel:[0,1,1]
	v_cvt_pk_bf16_f32 v24, v48, v49
	v_cvt_pk_bf16_f32 v28, v32, v33
	v_add_u32_e32 v32, 0x2000, v161
	ds_write2_b32 v32, v24, v28 offset0:128 offset1:196
	v_lshlrev_b32_e32 v33, 16, v29
	v_lshlrev_b32_e32 v32, 16, v25
	v_pk_fma_f32 v[32:33], v[56:57], s[44:45], v[32:33] op_sel_hi:[1,0,1] neg_lo:[1,0,0] neg_hi:[1,0,0]
	v_and_b32_e32 v29, 0xffff0000, v29
	v_and_b32_e32 v28, 0xffff0000, v25
	v_pk_mul_f32 v[32:33], v[32:33], v[58:59]
	v_pk_fma_f32 v[24:25], v[56:57], s[44:45], v[28:29] op_sel_hi:[1,0,1] neg_lo:[1,0,0] neg_hi:[1,0,0]
	v_pk_fma_f32 v[32:33], v[32:33], v[34:35], v[42:43] op_sel_hi:[1,0,0]
	v_pk_mul_f32 v[24:25], v[24:25], v[58:59]
	v_mov_b32_e32 v28, v35
	v_mov_b32_e32 v34, v43
	v_pk_fma_f32 v[24:25], v[24:25], v[28:29], v[34:35] op_sel_hi:[1,0,0]
	v_cvt_pk_bf16_f32 v28, v32, v33
	v_cvt_pk_bf16_f32 v24, v24, v25
	v_add_u32_e32 v48, 0x2400, v161
	ds_write2_b32 v48, v28, v24 offset0:8 offset1:76
	v_lshlrev_b32_e32 v25, 16, v30
	v_lshlrev_b32_e32 v24, 16, v26
	v_and_b32_e32 v29, 0xffff0000, v30
	v_and_b32_e32 v28, 0xffff0000, v26
	v_pk_fma_f32 v[24:25], v[56:57], s[44:45], v[24:25] op_sel_hi:[1,0,1] neg_lo:[1,0,0] neg_hi:[1,0,0]
	v_pk_fma_f32 v[28:29], v[56:57], s[44:45], v[28:29] op_sel_hi:[1,0,1] neg_lo:[1,0,0] neg_hi:[1,0,0]
	v_pk_mul_f32 v[24:25], v[24:25], v[58:59]
	v_pk_mul_f32 v[28:29], v[28:29], v[58:59]
	s_waitcnt lgkmcnt(2)
	v_pk_fma_f32 v[24:25], v[24:25], v[36:37], v[44:45] op_sel_hi:[1,0,0]
	v_pk_fma_f32 v[28:29], v[28:29], v[36:37], v[44:45] op_sel:[0,1,1]
	v_cvt_pk_bf16_f32 v24, v24, v25
	v_cvt_pk_bf16_f32 v25, v28, v29
	v_add_u32_e32 v44, 0x2800, v161
	ds_write2_b32 v44, v24, v25 offset0:160 offset1:228
	v_lshlrev_b32_e32 v25, 16, v31
	v_lshlrev_b32_e32 v24, 16, v27
	v_and_b32_e32 v29, 0xffff0000, v31
	v_and_b32_e32 v28, 0xffff0000, v27
	v_pk_fma_f32 v[24:25], v[56:57], s[44:45], v[24:25] op_sel_hi:[1,0,1] neg_lo:[1,0,0] neg_hi:[1,0,0]
	v_pk_fma_f32 v[26:27], v[56:57], s[44:45], v[28:29] op_sel_hi:[1,0,1] neg_lo:[1,0,0] neg_hi:[1,0,0]
	v_pk_mul_f32 v[24:25], v[24:25], v[58:59]
	v_pk_mul_f32 v[26:27], v[26:27], v[58:59]
	v_mov_b32_e32 v28, v39
	v_mov_b32_e32 v30, v47
	v_pk_fma_f32 v[24:25], v[24:25], v[38:39], v[46:47] op_sel_hi:[1,0,0]
	v_pk_fma_f32 v[26:27], v[26:27], v[28:29], v[30:31] op_sel_hi:[1,0,0]
	v_cvt_pk_bf16_f32 v24, v24, v25
	v_cvt_pk_bf16_f32 v25, v26, v27
	v_add_u32_e32 v45, 0x2c00, v161
	ds_write2_b32 v45, v24, v25 offset0:40 offset1:108
	ds_read_b128 v[24:27], v60 offset:160
	ds_read_b128 v[28:31], v60 offset:176
	ds_read_b128 v[32:35], v61 offset:160
	ds_read_b128 v[36:39], v61 offset:176
	v_lshlrev_b32_e32 v41, 16, v20
	v_lshlrev_b32_e32 v40, 16, v16
	v_and_b32_e32 v43, 0xffff0000, v20
	v_and_b32_e32 v42, 0xffff0000, v16
	v_pk_fma_f32 v[40:41], v[56:57], s[44:45], v[40:41] op_sel_hi:[1,0,1] neg_lo:[1,0,0] neg_hi:[1,0,0]
	v_pk_fma_f32 v[42:43], v[56:57], s[44:45], v[42:43] op_sel_hi:[1,0,1] neg_lo:[1,0,0] neg_hi:[1,0,0]
	v_pk_mul_f32 v[40:41], v[40:41], v[58:59]
	v_pk_mul_f32 v[42:43], v[42:43], v[58:59]
	s_waitcnt lgkmcnt(1)
	v_pk_fma_f32 v[40:41], v[40:41], v[24:25], v[32:33] op_sel_hi:[1,0,0]
	v_pk_fma_f32 v[24:25], v[42:43], v[24:25], v[32:33] op_sel:[0,1,1]
	v_cvt_pk_bf16_f32 v16, v40, v41
	v_cvt_pk_bf16_f32 v20, v24, v25
	v_add_u32_e32 v24, 0x3200, v161
	ds_write2_b32 v24, v16, v20 offset0:64 offset1:132
	v_lshlrev_b32_e32 v25, 16, v21
	v_lshlrev_b32_e32 v24, 16, v17
	v_pk_fma_f32 v[24:25], v[56:57], s[44:45], v[24:25] op_sel_hi:[1,0,1] neg_lo:[1,0,0] neg_hi:[1,0,0]
	v_and_b32_e32 v21, 0xffff0000, v21
	v_and_b32_e32 v20, 0xffff0000, v17
	v_pk_mul_f32 v[24:25], v[24:25], v[58:59]
	v_pk_fma_f32 v[16:17], v[56:57], s[44:45], v[20:21] op_sel_hi:[1,0,1] neg_lo:[1,0,0] neg_hi:[1,0,0]
	v_pk_fma_f32 v[24:25], v[24:25], v[26:27], v[34:35] op_sel_hi:[1,0,0]
	v_pk_mul_f32 v[16:17], v[16:17], v[58:59]
	v_mov_b32_e32 v20, v27
	v_mov_b32_e32 v26, v35
	v_pk_fma_f32 v[16:17], v[16:17], v[20:21], v[26:27] op_sel_hi:[1,0,0]
	v_cvt_pk_bf16_f32 v20, v24, v25
	v_cvt_pk_bf16_f32 v16, v16, v17
	v_add_u32_e32 v17, 0x3400, v161
	ds_write2_b32 v17, v20, v16 offset0:72 offset1:140
	v_lshlrev_b32_e32 v17, 16, v22
	v_lshlrev_b32_e32 v16, 16, v18
	v_and_b32_e32 v21, 0xffff0000, v22
	v_and_b32_e32 v20, 0xffff0000, v18
	v_pk_fma_f32 v[16:17], v[56:57], s[44:45], v[16:17] op_sel_hi:[1,0,1] neg_lo:[1,0,0] neg_hi:[1,0,0]
	v_pk_fma_f32 v[20:21], v[56:57], s[44:45], v[20:21] op_sel_hi:[1,0,1] neg_lo:[1,0,0] neg_hi:[1,0,0]
	v_pk_mul_f32 v[16:17], v[16:17], v[58:59]
	v_pk_mul_f32 v[20:21], v[20:21], v[58:59]
	s_waitcnt lgkmcnt(2)
	v_pk_fma_f32 v[16:17], v[16:17], v[28:29], v[36:37] op_sel_hi:[1,0,0]
	v_pk_fma_f32 v[20:21], v[20:21], v[28:29], v[36:37] op_sel:[0,1,1]
	v_cvt_pk_bf16_f32 v16, v16, v17
	v_cvt_pk_bf16_f32 v17, v20, v21
	v_add_u32_e32 v18, 0x3a00, v161
	ds_write2_b32 v18, v16, v17 offset0:96 offset1:164
	v_lshlrev_b32_e32 v17, 16, v23
	v_lshlrev_b32_e32 v16, 16, v19
	v_and_b32_e32 v21, 0xffff0000, v23
	v_and_b32_e32 v20, 0xffff0000, v19
	v_pk_fma_f32 v[16:17], v[56:57], s[44:45], v[16:17] op_sel_hi:[1,0,1] neg_lo:[1,0,0] neg_hi:[1,0,0]
	v_pk_fma_f32 v[18:19], v[56:57], s[44:45], v[20:21] op_sel_hi:[1,0,1] neg_lo:[1,0,0] neg_hi:[1,0,0]
	v_pk_mul_f32 v[16:17], v[16:17], v[58:59]
	v_pk_mul_f32 v[18:19], v[18:19], v[58:59]
	v_mov_b32_e32 v20, v31
	v_mov_b32_e32 v22, v39
	v_pk_fma_f32 v[16:17], v[16:17], v[30:31], v[38:39] op_sel_hi:[1,0,0]
	v_pk_fma_f32 v[18:19], v[18:19], v[20:21], v[22:23] op_sel_hi:[1,0,0]
	v_cvt_pk_bf16_f32 v16, v16, v17
	v_cvt_pk_bf16_f32 v17, v18, v19
	v_add_u32_e32 v18, 0x3c00, v161
	ds_write2_b32 v18, v16, v17 offset0:104 offset1:172
	ds_read_b128 v[16:19], v60 offset:192
	ds_read_b128 v[20:23], v60 offset:208
	ds_read_b128 v[24:27], v61 offset:192
	ds_read_b128 v[28:31], v61 offset:208
	v_lshlrev_b32_e32 v33, 16, v12
	v_lshlrev_b32_e32 v32, 16, v8
	v_and_b32_e32 v35, 0xffff0000, v12
	v_and_b32_e32 v34, 0xffff0000, v8
	v_pk_fma_f32 v[32:33], v[56:57], s[44:45], v[32:33] op_sel_hi:[1,0,1] neg_lo:[1,0,0] neg_hi:[1,0,0]
	v_pk_fma_f32 v[34:35], v[56:57], s[44:45], v[34:35] op_sel_hi:[1,0,1] neg_lo:[1,0,0] neg_hi:[1,0,0]
	v_pk_mul_f32 v[32:33], v[32:33], v[58:59]
	v_pk_mul_f32 v[34:35], v[34:35], v[58:59]
	s_waitcnt lgkmcnt(1)
	v_pk_fma_f32 v[32:33], v[32:33], v[16:17], v[24:25] op_sel_hi:[1,0,0]
	v_pk_fma_f32 v[16:17], v[34:35], v[16:17], v[24:25] op_sel:[0,1,1]
	v_cvt_pk_bf16_f32 v8, v32, v33
	v_cvt_pk_bf16_f32 v12, v16, v17
	v_lshlrev_b32_e32 v17, 16, v13
	v_lshlrev_b32_e32 v16, 16, v9
	ds_write2_b32 v48, v8, v12 offset0:144 offset1:212
	v_pk_fma_f32 v[16:17], v[56:57], s[44:45], v[16:17] op_sel_hi:[1,0,1] neg_lo:[1,0,0] neg_hi:[1,0,0]
	v_and_b32_e32 v13, 0xffff0000, v13
	v_and_b32_e32 v12, 0xffff0000, v9
	v_pk_mul_f32 v[16:17], v[16:17], v[58:59]
	v_pk_fma_f32 v[8:9], v[56:57], s[44:45], v[12:13] op_sel_hi:[1,0,1] neg_lo:[1,0,0] neg_hi:[1,0,0]
	v_pk_fma_f32 v[16:17], v[16:17], v[18:19], v[26:27] op_sel_hi:[1,0,0]
	v_pk_mul_f32 v[8:9], v[8:9], v[58:59]
	v_mov_b32_e32 v12, v19
	v_mov_b32_e32 v18, v27
	v_pk_fma_f32 v[8:9], v[8:9], v[12:13], v[18:19] op_sel_hi:[1,0,0]
	v_cvt_pk_bf16_f32 v12, v16, v17
	v_cvt_pk_bf16_f32 v8, v8, v9
	ds_write2_b32 v44, v12, v8 offset0:24 offset1:92
	v_lshlrev_b32_e32 v9, 16, v14
	v_lshlrev_b32_e32 v8, 16, v10
	v_and_b32_e32 v13, 0xffff0000, v14
	v_and_b32_e32 v12, 0xffff0000, v10
	v_pk_fma_f32 v[8:9], v[56:57], s[44:45], v[8:9] op_sel_hi:[1,0,1] neg_lo:[1,0,0] neg_hi:[1,0,0]
	v_pk_fma_f32 v[12:13], v[56:57], s[44:45], v[12:13] op_sel_hi:[1,0,1] neg_lo:[1,0,0] neg_hi:[1,0,0]
	v_pk_mul_f32 v[8:9], v[8:9], v[58:59]
	v_pk_mul_f32 v[12:13], v[12:13], v[58:59]
	s_waitcnt lgkmcnt(2)
	v_pk_fma_f32 v[8:9], v[8:9], v[20:21], v[28:29] op_sel_hi:[1,0,0]
	v_pk_fma_f32 v[12:13], v[12:13], v[20:21], v[28:29] op_sel:[0,1,1]
	v_cvt_pk_bf16_f32 v8, v8, v9
	v_cvt_pk_bf16_f32 v9, v12, v13
	ds_write2_b32 v45, v8, v9 offset0:176 offset1:244
	v_lshlrev_b32_e32 v9, 16, v15
	v_lshlrev_b32_e32 v8, 16, v11
	v_and_b32_e32 v13, 0xffff0000, v15
	v_and_b32_e32 v12, 0xffff0000, v11
	v_pk_fma_f32 v[8:9], v[56:57], s[44:45], v[8:9] op_sel_hi:[1,0,1] neg_lo:[1,0,0] neg_hi:[1,0,0]
	v_pk_fma_f32 v[10:11], v[56:57], s[44:45], v[12:13] op_sel_hi:[1,0,1] neg_lo:[1,0,0] neg_hi:[1,0,0]
	v_pk_mul_f32 v[8:9], v[8:9], v[58:59]
	v_pk_mul_f32 v[10:11], v[10:11], v[58:59]
	v_mov_b32_e32 v12, v23
	v_mov_b32_e32 v14, v31
	v_pk_fma_f32 v[8:9], v[8:9], v[22:23], v[30:31] op_sel_hi:[1,0,0]
	v_pk_fma_f32 v[10:11], v[10:11], v[12:13], v[14:15] op_sel_hi:[1,0,0]
	v_cvt_pk_bf16_f32 v8, v8, v9
	v_cvt_pk_bf16_f32 v9, v10, v11
	v_add_u32_e32 v10, 0x3000, v161
	ds_write2_b32 v10, v8, v9 offset0:56 offset1:124
	ds_read_b128 v[8:11], v60 offset:224
	ds_read_b128 v[12:15], v60 offset:240
	ds_read_b128 v[16:19], v61 offset:224
	ds_read_b128 v[20:23], v61 offset:240
	v_lshlrev_b32_e32 v25, 16, v4
	v_lshlrev_b32_e32 v24, 16, v0
	v_and_b32_e32 v27, 0xffff0000, v4
	v_and_b32_e32 v26, 0xffff0000, v0
	v_pk_fma_f32 v[24:25], v[56:57], s[44:45], v[24:25] op_sel_hi:[1,0,1] neg_lo:[1,0,0] neg_hi:[1,0,0]
	v_pk_fma_f32 v[26:27], v[56:57], s[44:45], v[26:27] op_sel_hi:[1,0,1] neg_lo:[1,0,0] neg_hi:[1,0,0]
	v_pk_mul_f32 v[24:25], v[24:25], v[58:59]
	v_pk_mul_f32 v[26:27], v[26:27], v[58:59]
	s_waitcnt lgkmcnt(1)
	v_pk_fma_f32 v[24:25], v[24:25], v[8:9], v[16:17] op_sel_hi:[1,0,0]
	v_pk_fma_f32 v[8:9], v[26:27], v[8:9], v[16:17] op_sel:[0,1,1]
	v_cvt_pk_bf16_f32 v0, v24, v25
	v_cvt_pk_bf16_f32 v4, v8, v9
	v_add_u32_e32 v8, 0x3600, v161
	ds_write2_b32 v8, v0, v4 offset0:80 offset1:148
	v_lshlrev_b32_e32 v9, 16, v5
	v_lshlrev_b32_e32 v8, 16, v1
	v_pk_fma_f32 v[8:9], v[56:57], s[44:45], v[8:9] op_sel_hi:[1,0,1] neg_lo:[1,0,0] neg_hi:[1,0,0]
	v_and_b32_e32 v5, 0xffff0000, v5
	v_and_b32_e32 v4, 0xffff0000, v1
	v_pk_mul_f32 v[8:9], v[8:9], v[58:59]
	v_pk_fma_f32 v[0:1], v[56:57], s[44:45], v[4:5] op_sel_hi:[1,0,1] neg_lo:[1,0,0] neg_hi:[1,0,0]
	v_pk_fma_f32 v[8:9], v[8:9], v[10:11], v[18:19] op_sel_hi:[1,0,0]
	v_pk_mul_f32 v[0:1], v[0:1], v[58:59]
	v_mov_b32_e32 v4, v11
	v_mov_b32_e32 v10, v19
	v_pk_fma_f32 v[0:1], v[0:1], v[4:5], v[10:11] op_sel_hi:[1,0,0]
	v_cvt_pk_bf16_f32 v4, v8, v9
	v_cvt_pk_bf16_f32 v0, v0, v1
	v_add_u32_e32 v1, 0x3800, v161
	ds_write2_b32 v1, v4, v0 offset0:88 offset1:156
	v_lshlrev_b32_e32 v1, 16, v6
	v_lshlrev_b32_e32 v0, 16, v2
	v_and_b32_e32 v5, 0xffff0000, v6
	v_and_b32_e32 v4, 0xffff0000, v2
	v_pk_fma_f32 v[0:1], v[56:57], s[44:45], v[0:1] op_sel_hi:[1,0,1] neg_lo:[1,0,0] neg_hi:[1,0,0]
	v_pk_fma_f32 v[4:5], v[56:57], s[44:45], v[4:5] op_sel_hi:[1,0,1] neg_lo:[1,0,0] neg_hi:[1,0,0]
	v_pk_mul_f32 v[0:1], v[0:1], v[58:59]
	v_pk_mul_f32 v[4:5], v[4:5], v[58:59]
	s_waitcnt lgkmcnt(2)
	v_pk_fma_f32 v[0:1], v[0:1], v[12:13], v[20:21] op_sel_hi:[1,0,0]
	v_pk_fma_f32 v[4:5], v[4:5], v[12:13], v[20:21] op_sel:[0,1,1]
	v_cvt_pk_bf16_f32 v0, v0, v1
	v_cvt_pk_bf16_f32 v1, v4, v5
	v_add_u32_e32 v2, 0x3e00, v161
	ds_write2_b32 v2, v0, v1 offset0:112 offset1:180
	v_lshlrev_b32_e32 v1, 16, v7
	v_lshlrev_b32_e32 v0, 16, v3
	v_and_b32_e32 v5, 0xffff0000, v7
	v_and_b32_e32 v4, 0xffff0000, v3
	v_pk_fma_f32 v[0:1], v[56:57], s[44:45], v[0:1] op_sel_hi:[1,0,1] neg_lo:[1,0,0] neg_hi:[1,0,0]
	v_pk_fma_f32 v[2:3], v[56:57], s[44:45], v[4:5] op_sel_hi:[1,0,1] neg_lo:[1,0,0] neg_hi:[1,0,0]
	v_pk_mul_f32 v[0:1], v[0:1], v[58:59]
	v_pk_mul_f32 v[2:3], v[2:3], v[58:59]
	v_mov_b32_e32 v4, v15
	v_mov_b32_e32 v6, v23
	v_pk_fma_f32 v[0:1], v[0:1], v[14:15], v[22:23] op_sel_hi:[1,0,0]
	v_pk_fma_f32 v[2:3], v[2:3], v[4:5], v[6:7] op_sel_hi:[1,0,0]
	v_cvt_pk_bf16_f32 v0, v0, v1
	v_cvt_pk_bf16_f32 v1, v2, v3
	v_add_u32_e32 v2, 0x4000, v161
	ds_write2_b32 v2, v0, v1 offset0:120 offset1:188
	v_add_u32_e32 v0, v163, v169
	ds_read_b128 v[100:103], v0
	ds_read_b128 v[96:99], v0 offset:32
	ds_read_b128 v[92:95], v0 offset:64
	ds_read_b128 v[88:91], v0 offset:96
	ds_read_b128 v[84:87], v0 offset:128
	ds_read_b128 v[80:83], v0 offset:160
	ds_read_b128 v[72:75], v0 offset:192
	ds_read_b128 v[64:67], v0 offset:224
	v_add_u32_e32 v0, v163, v171
	v_or_b32_e32 v1, s20, v167
	ds_read_b128 v[124:127], v0
	ds_read_b128 v[120:123], v0 offset:32
	ds_read_b128 v[116:119], v0 offset:64
	ds_read_b128 v[112:115], v0 offset:96
	ds_read_b128 v[108:111], v0 offset:128
	ds_read_b128 v[104:107], v0 offset:160
	ds_read_b128 v[76:79], v0 offset:192
	ds_read_b128 v[68:71], v0 offset:224
	v_or_b32_e32 v0, s19, v157
	v_lshlrev_b32_e32 v192, 1, v1
	v_lshl_add_u64 v[206:207], s[36:37], 0, v[192:193]
	v_lshl_add_u64 v[204:205], s[80:81], 0, v[192:193]
	v_lshl_add_u64 v[202:203], s[4:5], 0, v[192:193]
	v_lshlrev_b32_e32 v192, 8, v0
	v_lshl_add_u64 v[128:129], v[158:159], 0, v[192:193]
	global_load_dwordx4 v[0:3], v[128:129], off
	global_load_dwordx4 v[32:35], v[128:129], off offset:32
	v_add_co_u32_e32 v4, vcc, s57, v128
	v_readlane_b32 s20, v253, 61
	s_nop 0
	v_addc_co_u32_e32 v5, vcc, 0, v129, vcc
	global_load_dwordx4 v[36:39], v[4:5], off
	global_load_dwordx4 v[130:133], v[4:5], off offset:32
	global_load_dwordx4 v[134:137], v[4:5], off offset:64
	global_load_dwordx4 v[138:141], v[4:5], off offset:96
	v_readlane_b32 s21, v253, 62
	s_waitcnt vmcnt(3) lgkmcnt(14)
	v_mfma_f32_32x32x16_bf16 v[48:63], v[100:103], v[36:39], 0
	v_and_b32_e32 v4, 0xffff0000, v0
	v_cndmask_b32_e64 v4, v0, v4, s[52:53]
	v_and_b32_e32 v4, 0xffff, v4
	v_cndmask_b32_e64 v0, v4, v0, s[20:21]
	v_readlane_b32 s20, v253, 59
	v_and_b32_e32 v4, 0xffff0000, v1
	v_readlane_b32 s21, v253, 60
	v_and_b32_e32 v40, 0xffff0000, v32
	s_waitcnt vmcnt(2)
	v_mfma_f32_32x32x16_bf16 v[48:63], v[96:99], v[130:133], v[48:63]
	v_cndmask_b32_e64 v1, v1, v4, s[20:21]
	v_readlane_b32 s20, v253, 57
	v_and_b32_e32 v4, 0xffff, v1
	v_readlane_b32 s21, v253, 58
	s_nop 1
	v_cndmask_b32_e64 v1, v1, v4, s[20:21]
	v_readlane_b32 s20, v253, 55
	v_and_b32_e32 v4, 0xffff0000, v2
	v_readlane_b32 s21, v253, 56
	s_nop 1
	v_cndmask_b32_e64 v2, v2, v4, s[20:21]
	v_readlane_b32 s20, v253, 53
	v_and_b32_e32 v4, 0xffff, v2
	v_readlane_b32 s21, v253, 54
	s_nop 1
	v_cndmask_b32_e64 v2, v2, v4, s[20:21]
	v_readlane_b32 s20, v254, 13
	v_readlane_b32 s21, v254, 14
	v_and_b32_e32 v4, 0xffff0000, v3
	v_cndmask_b32_e64 v3, v3, v4, s[86:87]
	v_cndmask_b32_e64 v32, v32, v40, s[20:21]
	v_readlane_b32 s20, v254, 11
	v_and_b32_e32 v40, 0xffff, v32
	v_readlane_b32 s21, v254, 12
	v_and_b32_e32 v4, 0xffff, v3
	v_cndmask_b32_e64 v3, v3, v4, s[84:85]
	v_cndmask_b32_e64 v32, v32, v40, s[20:21]
	v_readlane_b32 s20, v254, 9
	v_and_b32_e32 v40, 0xffff0000, v33
	v_readlane_b32 s21, v254, 10
	v_mfma_f32_32x32x16_bf16 v[16:31], v[100:103], v[0:3], 0
	s_nop 0
	v_cndmask_b32_e64 v33, v33, v40, s[20:21]
	v_readlane_b32 s20, v254, 7
	v_and_b32_e32 v40, 0xffff, v33
	v_readlane_b32 s21, v254, 8
	s_nop 1
	v_cndmask_b32_e64 v33, v33, v40, s[20:21]
	v_readlane_b32 s20, v254, 5
	s_waitcnt lgkmcnt(7)
	v_mfma_f32_32x32x16_bf16 v[0:15], v[124:127], v[0:3], 0
	v_and_b32_e32 v40, 0xffff0000, v34
	v_readlane_b32 s21, v254, 6
	s_nop 1
	v_cndmask_b32_e64 v34, v34, v40, s[20:21]
	v_readlane_b32 s20, v254, 3
	v_and_b32_e32 v40, 0xffff, v34
	v_readlane_b32 s21, v254, 4
	s_nop 1
	v_cndmask_b32_e64 v34, v34, v40, s[20:21]
	v_readlane_b32 s20, v254, 1
	v_and_b32_e32 v40, 0xffff0000, v35
	v_readlane_b32 s21, v254, 2
	s_nop 1
	v_cndmask_b32_e64 v35, v35, v40, s[20:21]
	v_readlane_b32 s20, v253, 63
	v_and_b32_e32 v40, 0xffff, v35
	v_readlane_b32 s21, v254, 0
	s_nop 1
	v_cndmask_b32_e64 v35, v35, v40, s[20:21]
	v_readlane_b32 s20, v254, 29
	v_readlane_b32 s21, v254, 30
	v_mfma_f32_32x32x16_bf16 v[16:31], v[96:99], v[32:35], v[16:31]
	s_waitcnt lgkmcnt(6)
	v_mfma_f32_32x32x16_bf16 v[0:15], v[120:123], v[32:35], v[0:15]
	s_nop 9
	ds_write_b128 v175, v[16:19]
	ds_write_b128 v175, v[20:23] offset:16
	ds_write_b128 v175, v[24:27] offset:32
	ds_write_b128 v175, v[28:31] offset:48
	ds_write_b128 v175, v[0:3] offset:128
	ds_write_b128 v175, v[4:7] offset:144
	ds_write_b128 v175, v[8:11] offset:160
	ds_write_b128 v175, v[12:15] offset:176
	v_or_b32_e32 v8, s19, v160
	v_lshlrev_b32_e32 v179, 2, v8
	v_lshlrev_b64 v[8:9], 11, v[154:155]
	v_mfma_f32_32x32x16_bf16 v[32:47], v[124:127], v[36:39], 0
	v_lshl_add_u64 v[10:11], v[206:207], 0, v[8:9]
	v_lshl_add_u64 v[8:9], v[204:205], 0, v[8:9]
	v_mfma_f32_32x32x16_bf16 v[32:47], v[120:123], v[130:133], v[32:47]
	s_waitcnt vmcnt(1)
	v_and_b32_e32 v130, 0xffff0000, v134
	v_cndmask_b32_e64 v130, v134, v130, s[20:21]
	v_readlane_b32 s20, v254, 27
	v_and_b32_e32 v131, 0xffff, v130
	v_readlane_b32 s21, v254, 28
	s_nop 1
	v_cndmask_b32_e64 v130, v130, v131, s[20:21]
	v_readlane_b32 s20, v254, 25
	v_and_b32_e32 v131, 0xffff0000, v135
	v_readlane_b32 s21, v254, 26
	s_nop 1
	v_cndmask_b32_e64 v131, v135, v131, s[20:21]
	v_readlane_b32 s20, v254, 23
	v_and_b32_e32 v132, 0xffff, v131
	v_readlane_b32 s21, v254, 24
	s_nop 1
	v_cndmask_b32_e64 v131, v131, v132, s[20:21]
	v_readlane_b32 s20, v254, 21
	v_and_b32_e32 v132, 0xffff0000, v136
	v_readlane_b32 s21, v254, 22
	s_nop 1
	v_cndmask_b32_e64 v132, v136, v132, s[20:21]
	v_readlane_b32 s20, v254, 19
	v_and_b32_e32 v133, 0xffff, v132
	v_readlane_b32 s21, v254, 20
	v_or_b32_e32 v136, s14, v172
	s_nop 0
	v_cndmask_b32_e64 v132, v132, v133, s[20:21]
	v_readlane_b32 s20, v254, 17
	v_and_b32_e32 v133, 0xffff0000, v137
	v_readlane_b32 s21, v254, 18
	s_nop 1
	v_cndmask_b32_e64 v133, v137, v133, s[20:21]
	v_readlane_b32 s20, v254, 15
	v_and_b32_e32 v134, 0xffff, v133
	v_readlane_b32 s21, v254, 16
	v_mov_b32_e32 v137, s15
	s_nop 0
	v_cndmask_b32_e64 v133, v133, v134, s[20:21]
	v_readlane_b32 s20, v254, 45
	v_readlane_b32 s21, v254, 46
	v_mfma_f32_32x32x16_bf16 v[48:63], v[92:95], v[130:133], v[48:63]
	s_waitcnt lgkmcnt(13)
	v_mfma_f32_32x32x16_bf16 v[32:47], v[116:119], v[130:133], v[32:47]
	s_waitcnt vmcnt(0)
	v_and_b32_e32 v130, 0xffff0000, v138
	v_cndmask_b32_e64 v130, v138, v130, s[20:21]
	v_readlane_b32 s20, v254, 43
	v_and_b32_e32 v131, 0xffff, v130
	v_readlane_b32 s21, v254, 44
	s_nop 1
	v_cndmask_b32_e64 v130, v130, v131, s[20:21]
	v_readlane_b32 s20, v254, 41
	v_and_b32_e32 v131, 0xffff0000, v139
	v_readlane_b32 s21, v254, 42
	s_nop 1
	v_cndmask_b32_e64 v131, v139, v131, s[20:21]
	v_readlane_b32 s20, v254, 39
	v_and_b32_e32 v132, 0xffff, v131
	v_readlane_b32 s21, v254, 40
	s_nop 1
	v_cndmask_b32_e64 v131, v131, v132, s[20:21]
	v_readlane_b32 s20, v254, 37
	v_and_b32_e32 v132, 0xffff0000, v140
	v_readlane_b32 s21, v254, 38
	s_nop 1
	v_cndmask_b32_e64 v132, v140, v132, s[20:21]
	v_readlane_b32 s20, v254, 35
	v_and_b32_e32 v133, 0xffff, v132
	v_readlane_b32 s21, v254, 36
	v_or_b32_e32 v140, s14, v170
	s_nop 0
	v_cndmask_b32_e64 v132, v132, v133, s[20:21]
	v_readlane_b32 s20, v254, 33
	v_and_b32_e32 v133, 0xffff0000, v141
	v_readlane_b32 s21, v254, 34
	s_nop 1
	v_cndmask_b32_e64 v133, v141, v133, s[20:21]
	v_readlane_b32 s20, v254, 31
	v_and_b32_e32 v134, 0xffff, v133
	v_readlane_b32 s21, v254, 32
	v_mov_b32_e32 v141, s15
	s_nop 0
	v_cndmask_b32_e64 v133, v133, v134, s[20:21]
	v_readlane_b32 s20, v254, 59
	v_readlane_b32 s21, v254, 60
	v_mfma_f32_32x32x16_bf16 v[48:63], v[88:91], v[130:133], v[48:63]
	s_waitcnt lgkmcnt(12)
	v_mfma_f32_32x32x16_bf16 v[32:47], v[112:115], v[130:133], v[32:47]
	v_mov_b32_e32 v131, s15
	v_or_b32_e32 v130, s14, v160
	v_lshlrev_b64 v[0:1], 11, v[130:131]
	s_nop 6
	ds_write_b128 v177, v[48:51]
	ds_write_b128 v177, v[52:55] offset:16
	ds_write_b128 v177, v[56:59] offset:32
	ds_write_b128 v177, v[60:63] offset:48
	ds_write_b128 v177, v[32:35] offset:128
	ds_write_b128 v177, v[36:39] offset:144
	ds_write_b128 v177, v[40:43] offset:160
	ds_write_b128 v177, v[44:47] offset:176
	v_lshl_add_u64 v[2:3], v[206:207], 0, v[0:1]
	v_lshl_add_u64 v[0:1], v[204:205], 0, v[0:1]
	global_load_dwordx4 v[4:7], v[2:3], off nt
	global_load_dword v208, v179, s[12:13]
	global_load_dwordx4 v[52:55], v[10:11], off nt
	v_mov_b32_e32 v133, s15
	global_load_dwordx4 v[0:3], v[0:1], off nt
	s_nop 0
	global_load_dwordx4 v[48:51], v[8:9], off nt
	global_load_dword v192, v179, s[12:13] offset:32
	v_lshlrev_b64 v[8:9], 11, v[150:151]
	v_lshl_add_u64 v[10:11], v[206:207], 0, v[8:9]
	v_lshl_add_u64 v[8:9], v[204:205], 0, v[8:9]
	global_load_dwordx4 v[44:47], v[10:11], off nt
	global_load_dwordx4 v[40:43], v[8:9], off nt
	global_load_dword v152, v179, s[12:13] offset:64
	v_lshlrev_b64 v[8:9], 11, v[146:147]
	v_lshl_add_u64 v[10:11], v[206:207], 0, v[8:9]
	v_lshl_add_u64 v[8:9], v[204:205], 0, v[8:9]
	global_load_dwordx4 v[36:39], v[10:11], off nt
	global_load_dwordx4 v[32:35], v[8:9], off nt
	global_load_dword v148, v179, s[12:13] offset:96
	v_lshlrev_b64 v[8:9], 11, v[140:141]
	v_lshl_add_u64 v[10:11], v[206:207], 0, v[8:9]
	v_lshl_add_u64 v[8:9], v[204:205], 0, v[8:9]
	global_load_dwordx4 v[28:31], v[10:11], off nt
	global_load_dwordx4 v[24:27], v[8:9], off nt
	global_load_dword v142, v179, s[12:13] offset:128
	v_lshlrev_b64 v[8:9], 11, v[136:137]
	v_lshl_add_u64 v[10:11], v[206:207], 0, v[8:9]
	v_lshl_add_u64 v[8:9], v[204:205], 0, v[8:9]
	v_or_b32_e32 v132, s14, v174
	global_load_dwordx4 v[20:23], v[10:11], off nt
	global_load_dwordx4 v[16:19], v[8:9], off nt
	global_load_dword v138, v179, s[12:13] offset:160
	v_lshlrev_b64 v[8:9], 11, v[132:133]
	v_lshlrev_b64 v[60:61], 11, v[144:145]
	v_lshl_add_u64 v[10:11], v[206:207], 0, v[8:9]
	v_lshl_add_u64 v[8:9], v[204:205], 0, v[8:9]
	v_lshl_add_u64 v[56:57], v[206:207], 0, v[60:61]
	v_lshl_add_u64 v[60:61], v[204:205], 0, v[60:61]
	global_load_dwordx4 v[12:15], v[10:11], off nt
	s_nop 0
	global_load_dwordx4 v[8:11], v[8:9], off nt
	s_nop 0
	global_load_dword v134, v179, s[12:13] offset:192
	s_nop 0
	global_load_dwordx4 v[56:59], v[56:57], off nt
	s_nop 0
	global_load_dwordx4 v[60:63], v[60:61], off nt
	s_nop 0
	global_load_dword v210, v179, s[12:13] offset:224
	s_waitcnt vmcnt(1)
	ds_read_b128 v[212:215], v173
	ds_read_b128 v[216:219], v173 offset:16
	v_lshlrev_b32_e32 v196, 16, v4
	v_and_b32_e32 v197, 0xffff0000, v4
	v_lshlrev_b32_e32 v4, 16, v5
	s_waitcnt lgkmcnt(1)
	v_pk_add_f32 v[212:213], v[208:209], v[212:213] op_sel_hi:[0,1]
	v_pk_mul_f32 v[196:197], v[212:213], v[196:197]
	v_lshlrev_b32_e32 v212, 16, v0
	v_and_b32_e32 v213, 0xffff0000, v0
	v_pk_mul_f32 v[196:197], v[196:197], v[212:213]
	v_and_b32_e32 v5, 0xffff0000, v5
	v_cvt_pk_bf16_f32 v0, v196, v197
	v_pk_add_f32 v[196:197], v[208:209], v[214:215] op_sel_hi:[0,1]
	v_pk_mul_f32 v[4:5], v[196:197], v[4:5]
	v_lshlrev_b32_e32 v196, 16, v1
	v_and_b32_e32 v197, 0xffff0000, v1
	v_pk_mul_f32 v[4:5], v[4:5], v[196:197]
	s_waitcnt lgkmcnt(0)
	v_pk_add_f32 v[196:197], v[208:209], v[216:217] op_sel_hi:[0,1]
	v_cvt_pk_bf16_f32 v1, v4, v5
	v_lshlrev_b32_e32 v4, 16, v6
	v_and_b32_e32 v5, 0xffff0000, v6
	v_pk_mul_f32 v[4:5], v[196:197], v[4:5]
	v_lshlrev_b32_e32 v196, 16, v2
	v_and_b32_e32 v197, 0xffff0000, v2
	v_pk_mul_f32 v[4:5], v[4:5], v[196:197]
	s_nop 0
	v_cvt_pk_bf16_f32 v2, v4, v5
	v_lshlrev_b32_e32 v4, 16, v7
	v_and_b32_e32 v5, 0xffff0000, v7
	v_pk_add_f32 v[6:7], v[208:209], v[218:219] op_sel_hi:[0,1]
	v_pk_mul_f32 v[4:5], v[6:7], v[4:5]
	v_lshlrev_b32_e32 v6, 16, v3
	v_and_b32_e32 v7, 0xffff0000, v3
	v_pk_mul_f32 v[4:5], v[4:5], v[6:7]
	s_nop 0
	v_cvt_pk_bf16_f32 v3, v4, v5
	v_lshlrev_b64 v[4:5], 12, v[130:131]
	v_lshl_add_u64 v[4:5], v[202:203], 0, v[4:5]
	global_store_dwordx4 v[4:5], v[0:3], off
	ds_read_b128 v[0:3], v173 offset:2176
	ds_read_b128 v[4:7], v173 offset:2192
	v_lshlrev_b32_e32 v130, 16, v52
	v_and_b32_e32 v131, 0xffff0000, v52
	v_lshlrev_b32_e32 v52, 16, v53
	s_waitcnt lgkmcnt(1)
	v_pk_add_f32 v[0:1], v[192:193], v[0:1] op_sel_hi:[0,1]
	v_and_b32_e32 v53, 0xffff0000, v53
	v_pk_add_f32 v[2:3], v[192:193], v[2:3] op_sel_hi:[0,1]
	v_pk_mul_f32 v[0:1], v[0:1], v[130:131]
	v_lshlrev_b32_e32 v130, 16, v48
	v_and_b32_e32 v131, 0xffff0000, v48
	v_pk_mul_f32 v[2:3], v[2:3], v[52:53]
	v_lshlrev_b32_e32 v48, 16, v49
	v_and_b32_e32 v49, 0xffff0000, v49
	v_pk_mul_f32 v[0:1], v[0:1], v[130:131]
	v_pk_mul_f32 v[2:3], v[2:3], v[48:49]
	v_cvt_pk_bf16_f32 v0, v0, v1
	v_cvt_pk_bf16_f32 v1, v2, v3
	v_lshlrev_b32_e32 v2, 16, v54
	v_and_b32_e32 v3, 0xffff0000, v54
	s_waitcnt lgkmcnt(0)
	v_pk_add_f32 v[4:5], v[192:193], v[4:5] op_sel_hi:[0,1]
	v_pk_mul_f32 v[2:3], v[4:5], v[2:3]
	v_lshlrev_b32_e32 v4, 16, v50
	v_and_b32_e32 v5, 0xffff0000, v50
	v_pk_mul_f32 v[2:3], v[2:3], v[4:5]
	v_lshlrev_b32_e32 v4, 16, v55
	v_and_b32_e32 v5, 0xffff0000, v55
	v_pk_add_f32 v[6:7], v[192:193], v[6:7] op_sel_hi:[0,1]
	v_pk_mul_f32 v[4:5], v[6:7], v[4:5]
	v_lshlrev_b32_e32 v6, 16, v51
	v_and_b32_e32 v7, 0xffff0000, v51
	v_pk_mul_f32 v[4:5], v[4:5], v[6:7]
	v_cvt_pk_bf16_f32 v2, v2, v3
	v_cvt_pk_bf16_f32 v3, v4, v5
	v_lshlrev_b64 v[4:5], 12, v[154:155]
	v_lshl_add_u64 v[4:5], v[202:203], 0, v[4:5]
	global_store_dwordx4 v[4:5], v[0:3], off
	ds_read_b128 v[0:3], v173 offset:4352
	ds_read_b128 v[4:7], v173 offset:4368
	v_lshlrev_b32_e32 v48, 16, v44
	v_and_b32_e32 v49, 0xffff0000, v44
	v_lshlrev_b32_e32 v44, 16, v45
	s_waitcnt lgkmcnt(1)
	v_pk_add_f32 v[0:1], v[152:153], v[0:1] op_sel_hi:[0,1]
	v_and_b32_e32 v45, 0xffff0000, v45
	v_pk_add_f32 v[2:3], v[152:153], v[2:3] op_sel_hi:[0,1]
	v_pk_mul_f32 v[0:1], v[0:1], v[48:49]
	v_lshlrev_b32_e32 v48, 16, v40
	v_and_b32_e32 v49, 0xffff0000, v40
	v_pk_mul_f32 v[2:3], v[2:3], v[44:45]
	v_lshlrev_b32_e32 v40, 16, v41
	v_and_b32_e32 v41, 0xffff0000, v41
	v_pk_mul_f32 v[0:1], v[0:1], v[48:49]
	v_pk_mul_f32 v[2:3], v[2:3], v[40:41]
	v_cvt_pk_bf16_f32 v0, v0, v1
	v_cvt_pk_bf16_f32 v1, v2, v3
	v_lshlrev_b32_e32 v2, 16, v46
	v_and_b32_e32 v3, 0xffff0000, v46
	s_waitcnt lgkmcnt(0)
	v_pk_add_f32 v[4:5], v[152:153], v[4:5] op_sel_hi:[0,1]
	v_pk_mul_f32 v[2:3], v[4:5], v[2:3]
	v_lshlrev_b32_e32 v4, 16, v42
	v_and_b32_e32 v5, 0xffff0000, v42
	v_pk_mul_f32 v[2:3], v[2:3], v[4:5]
	v_lshlrev_b32_e32 v4, 16, v47
	v_and_b32_e32 v5, 0xffff0000, v47
	v_pk_add_f32 v[6:7], v[152:153], v[6:7] op_sel_hi:[0,1]
	v_pk_mul_f32 v[4:5], v[6:7], v[4:5]
	v_lshlrev_b32_e32 v6, 16, v43
	v_and_b32_e32 v7, 0xffff0000, v43
	v_pk_mul_f32 v[4:5], v[4:5], v[6:7]
	v_cvt_pk_bf16_f32 v2, v2, v3
	v_cvt_pk_bf16_f32 v3, v4, v5
	v_lshlrev_b64 v[4:5], 12, v[150:151]
	v_lshl_add_u64 v[4:5], v[202:203], 0, v[4:5]
	global_store_dwordx4 v[4:5], v[0:3], off
	ds_read_b128 v[0:3], v173 offset:6528
	ds_read_b128 v[4:7], v173 offset:6544
	v_lshlrev_b32_e32 v40, 16, v36
	v_and_b32_e32 v41, 0xffff0000, v36
	v_lshlrev_b32_e32 v36, 16, v37
	s_waitcnt lgkmcnt(1)
	v_pk_add_f32 v[0:1], v[148:149], v[0:1] op_sel_hi:[0,1]
	v_and_b32_e32 v37, 0xffff0000, v37
	v_pk_add_f32 v[2:3], v[148:149], v[2:3] op_sel_hi:[0,1]
	v_pk_mul_f32 v[0:1], v[0:1], v[40:41]
	v_lshlrev_b32_e32 v40, 16, v32
	v_and_b32_e32 v41, 0xffff0000, v32
	v_pk_mul_f32 v[2:3], v[2:3], v[36:37]
	v_lshlrev_b32_e32 v32, 16, v33
	v_and_b32_e32 v33, 0xffff0000, v33
	v_pk_mul_f32 v[0:1], v[0:1], v[40:41]
	v_pk_mul_f32 v[2:3], v[2:3], v[32:33]
	v_cvt_pk_bf16_f32 v0, v0, v1
	v_cvt_pk_bf16_f32 v1, v2, v3
	v_lshlrev_b32_e32 v2, 16, v38
	v_and_b32_e32 v3, 0xffff0000, v38
	s_waitcnt lgkmcnt(0)
	v_pk_add_f32 v[4:5], v[148:149], v[4:5] op_sel_hi:[0,1]
	v_pk_mul_f32 v[2:3], v[4:5], v[2:3]
	v_lshlrev_b32_e32 v4, 16, v34
	v_and_b32_e32 v5, 0xffff0000, v34
	v_pk_mul_f32 v[2:3], v[2:3], v[4:5]
	v_lshlrev_b32_e32 v4, 16, v39
	v_and_b32_e32 v5, 0xffff0000, v39
	v_pk_add_f32 v[6:7], v[148:149], v[6:7] op_sel_hi:[0,1]
	v_pk_mul_f32 v[4:5], v[6:7], v[4:5]
	v_lshlrev_b32_e32 v6, 16, v35
	v_and_b32_e32 v7, 0xffff0000, v35
	v_pk_mul_f32 v[4:5], v[4:5], v[6:7]
	v_cvt_pk_bf16_f32 v2, v2, v3
	v_cvt_pk_bf16_f32 v3, v4, v5
	v_lshlrev_b64 v[4:5], 12, v[146:147]
	v_lshl_add_u64 v[4:5], v[202:203], 0, v[4:5]
	global_store_dwordx4 v[4:5], v[0:3], off
	ds_read_b128 v[0:3], v173 offset:8704
	ds_read_b128 v[4:7], v173 offset:8720
	v_lshlrev_b32_e32 v32, 16, v28
	v_and_b32_e32 v33, 0xffff0000, v28
	v_lshlrev_b32_e32 v28, 16, v29
	s_waitcnt lgkmcnt(1)
	v_pk_add_f32 v[0:1], v[142:143], v[0:1] op_sel_hi:[0,1]
	v_and_b32_e32 v29, 0xffff0000, v29
	v_pk_add_f32 v[2:3], v[142:143], v[2:3] op_sel_hi:[0,1]
	v_pk_mul_f32 v[0:1], v[0:1], v[32:33]
	v_lshlrev_b32_e32 v32, 16, v24
	v_and_b32_e32 v33, 0xffff0000, v24
	v_pk_mul_f32 v[2:3], v[2:3], v[28:29]
	v_lshlrev_b32_e32 v24, 16, v25
	v_and_b32_e32 v25, 0xffff0000, v25
	v_pk_mul_f32 v[0:1], v[0:1], v[32:33]
	v_pk_mul_f32 v[2:3], v[2:3], v[24:25]
	v_cvt_pk_bf16_f32 v0, v0, v1
	v_cvt_pk_bf16_f32 v1, v2, v3
	v_lshlrev_b32_e32 v2, 16, v30
	v_and_b32_e32 v3, 0xffff0000, v30
	s_waitcnt lgkmcnt(0)
	v_pk_add_f32 v[4:5], v[142:143], v[4:5] op_sel_hi:[0,1]
	v_pk_mul_f32 v[2:3], v[4:5], v[2:3]
	v_lshlrev_b32_e32 v4, 16, v26
	v_and_b32_e32 v5, 0xffff0000, v26
	v_pk_mul_f32 v[2:3], v[2:3], v[4:5]
	v_lshlrev_b32_e32 v4, 16, v31
	v_and_b32_e32 v5, 0xffff0000, v31
	v_pk_add_f32 v[6:7], v[142:143], v[6:7] op_sel_hi:[0,1]
	v_pk_mul_f32 v[4:5], v[6:7], v[4:5]
	v_lshlrev_b32_e32 v6, 16, v27
	v_and_b32_e32 v7, 0xffff0000, v27
	v_pk_mul_f32 v[4:5], v[4:5], v[6:7]
	v_cvt_pk_bf16_f32 v2, v2, v3
	v_cvt_pk_bf16_f32 v3, v4, v5
	v_lshlrev_b64 v[4:5], 12, v[140:141]
	v_lshl_add_u64 v[4:5], v[202:203], 0, v[4:5]
	global_store_dwordx4 v[4:5], v[0:3], off
	ds_read_b128 v[0:3], v173 offset:10880
	ds_read_b128 v[4:7], v173 offset:10896
	v_lshlrev_b32_e32 v24, 16, v20
	v_and_b32_e32 v25, 0xffff0000, v20
	v_lshlrev_b32_e32 v20, 16, v21
	s_waitcnt lgkmcnt(1)
	v_pk_add_f32 v[0:1], v[138:139], v[0:1] op_sel_hi:[0,1]
	v_and_b32_e32 v21, 0xffff0000, v21
	v_pk_add_f32 v[2:3], v[138:139], v[2:3] op_sel_hi:[0,1]
	v_pk_mul_f32 v[0:1], v[0:1], v[24:25]
	v_lshlrev_b32_e32 v24, 16, v16
	v_and_b32_e32 v25, 0xffff0000, v16
	v_pk_mul_f32 v[2:3], v[2:3], v[20:21]
	v_lshlrev_b32_e32 v16, 16, v17
	v_and_b32_e32 v17, 0xffff0000, v17
	v_pk_mul_f32 v[0:1], v[0:1], v[24:25]
	v_pk_mul_f32 v[2:3], v[2:3], v[16:17]
	v_cvt_pk_bf16_f32 v0, v0, v1
	v_cvt_pk_bf16_f32 v1, v2, v3
	v_lshlrev_b32_e32 v2, 16, v22
	v_and_b32_e32 v3, 0xffff0000, v22
	s_waitcnt lgkmcnt(0)
	v_pk_add_f32 v[4:5], v[138:139], v[4:5] op_sel_hi:[0,1]
	v_pk_mul_f32 v[2:3], v[4:5], v[2:3]
	v_lshlrev_b32_e32 v4, 16, v18
	v_and_b32_e32 v5, 0xffff0000, v18
	v_pk_mul_f32 v[2:3], v[2:3], v[4:5]
	v_lshlrev_b32_e32 v4, 16, v23
	v_and_b32_e32 v5, 0xffff0000, v23
	v_pk_add_f32 v[6:7], v[138:139], v[6:7] op_sel_hi:[0,1]
	v_pk_mul_f32 v[4:5], v[6:7], v[4:5]
	v_lshlrev_b32_e32 v6, 16, v19
	v_and_b32_e32 v7, 0xffff0000, v19
	v_pk_mul_f32 v[4:5], v[4:5], v[6:7]
	v_cvt_pk_bf16_f32 v2, v2, v3
	v_cvt_pk_bf16_f32 v3, v4, v5
	v_lshlrev_b64 v[4:5], 12, v[136:137]
	v_lshl_add_u64 v[4:5], v[202:203], 0, v[4:5]
	global_store_dwordx4 v[4:5], v[0:3], off
	ds_read_b128 v[0:3], v173 offset:13056
	ds_read_b128 v[4:7], v173 offset:13072
	v_lshlrev_b32_e32 v16, 16, v12
	v_and_b32_e32 v17, 0xffff0000, v12
	v_lshlrev_b32_e32 v12, 16, v13
	s_waitcnt lgkmcnt(1)
	v_pk_add_f32 v[0:1], v[134:135], v[0:1] op_sel_hi:[0,1]
	v_and_b32_e32 v13, 0xffff0000, v13
	v_pk_add_f32 v[2:3], v[134:135], v[2:3] op_sel_hi:[0,1]
	v_pk_mul_f32 v[0:1], v[0:1], v[16:17]
	v_lshlrev_b32_e32 v16, 16, v8
	v_and_b32_e32 v17, 0xffff0000, v8
	v_pk_mul_f32 v[2:3], v[2:3], v[12:13]
	v_lshlrev_b32_e32 v8, 16, v9
	v_and_b32_e32 v9, 0xffff0000, v9
	v_pk_mul_f32 v[0:1], v[0:1], v[16:17]
	v_pk_mul_f32 v[2:3], v[2:3], v[8:9]
	v_cvt_pk_bf16_f32 v0, v0, v1
	v_cvt_pk_bf16_f32 v1, v2, v3
	v_lshlrev_b32_e32 v2, 16, v14
	v_and_b32_e32 v3, 0xffff0000, v14
	s_waitcnt lgkmcnt(0)
	v_pk_add_f32 v[4:5], v[134:135], v[4:5] op_sel_hi:[0,1]
	v_pk_mul_f32 v[2:3], v[4:5], v[2:3]
	v_lshlrev_b32_e32 v4, 16, v10
	v_and_b32_e32 v5, 0xffff0000, v10
	v_pk_mul_f32 v[2:3], v[2:3], v[4:5]
	v_lshlrev_b32_e32 v4, 16, v15
	v_and_b32_e32 v5, 0xffff0000, v15
	v_pk_add_f32 v[6:7], v[134:135], v[6:7] op_sel_hi:[0,1]
	v_pk_mul_f32 v[4:5], v[6:7], v[4:5]
	v_lshlrev_b32_e32 v6, 16, v11
	v_and_b32_e32 v7, 0xffff0000, v11
	v_pk_mul_f32 v[4:5], v[4:5], v[6:7]
	v_cvt_pk_bf16_f32 v2, v2, v3
	v_cvt_pk_bf16_f32 v3, v4, v5
	v_lshlrev_b64 v[4:5], 12, v[132:133]
	v_lshl_add_u64 v[4:5], v[202:203], 0, v[4:5]
	global_store_dwordx4 v[4:5], v[0:3], off
	ds_read_b128 v[0:3], v173 offset:15232
	ds_read_b128 v[4:7], v173 offset:15248
	v_lshlrev_b32_e32 v8, 16, v56
	v_and_b32_e32 v9, 0xffff0000, v56
	s_waitcnt vmcnt(7) lgkmcnt(1)
	v_pk_add_f32 v[0:1], v[210:211], v[0:1] op_sel_hi:[0,1]
	v_pk_mul_f32 v[0:1], v[0:1], v[8:9]
	v_lshlrev_b32_e32 v8, 16, v60
	v_and_b32_e32 v9, 0xffff0000, v60
	v_pk_mul_f32 v[0:1], v[0:1], v[8:9]
	v_lshlrev_b32_e32 v8, 16, v57
	v_and_b32_e32 v9, 0xffff0000, v57
	v_pk_add_f32 v[2:3], v[210:211], v[2:3] op_sel_hi:[0,1]
	v_pk_mul_f32 v[2:3], v[2:3], v[8:9]
	v_lshlrev_b32_e32 v8, 16, v61
	v_and_b32_e32 v9, 0xffff0000, v61
	v_pk_mul_f32 v[2:3], v[2:3], v[8:9]
	v_cvt_pk_bf16_f32 v0, v0, v1
	v_cvt_pk_bf16_f32 v1, v2, v3
	v_lshlrev_b32_e32 v2, 16, v58
	v_and_b32_e32 v3, 0xffff0000, v58
	s_waitcnt lgkmcnt(0)
	v_pk_add_f32 v[4:5], v[210:211], v[4:5] op_sel_hi:[0,1]
	v_pk_mul_f32 v[2:3], v[4:5], v[2:3]
	v_lshlrev_b32_e32 v4, 16, v62
	v_and_b32_e32 v5, 0xffff0000, v62
	v_pk_mul_f32 v[2:3], v[2:3], v[4:5]
	v_lshlrev_b32_e32 v4, 16, v59
	v_and_b32_e32 v5, 0xffff0000, v59
	v_pk_add_f32 v[6:7], v[210:211], v[6:7] op_sel_hi:[0,1]
	v_pk_mul_f32 v[4:5], v[6:7], v[4:5]
	v_lshlrev_b32_e32 v6, 16, v63
	v_and_b32_e32 v7, 0xffff0000, v63
	v_pk_mul_f32 v[4:5], v[4:5], v[6:7]
	v_cvt_pk_bf16_f32 v2, v2, v3
	v_cvt_pk_bf16_f32 v3, v4, v5
	v_lshlrev_b64 v[4:5], 12, v[144:145]
	v_lshl_add_u64 v[4:5], v[202:203], 0, v[4:5]
	global_store_dwordx4 v[4:5], v[0:3], off
	v_add_co_u32_e32 v4, vcc, s25, v128
	s_nop 1
	v_addc_co_u32_e32 v5, vcc, 0, v129, vcc
	global_load_dwordx4 v[0:3], v[4:5], off
	global_load_dwordx4 v[52:55], v[4:5], off offset:32
	global_load_dwordx4 v[48:51], v[4:5], off offset:64
	global_load_dwordx4 v[44:47], v[4:5], off offset:96
	global_load_dwordx4 v[40:43], v[4:5], off offset:128
	global_load_dwordx4 v[36:39], v[4:5], off offset:160
	v_add_co_u32_e32 v4, vcc, s99, v128
	s_waitcnt vmcnt(5)
	v_mfma_f32_32x32x16_bf16 v[16:31], v[100:103], v[0:3], 0
	v_addc_co_u32_e32 v5, vcc, 0, v129, vcc
	global_load_dwordx4 v[32:35], v[4:5], off
	global_load_dwordx4 v[152:155], v[4:5], off offset:32
	global_load_dwordx4 v[148:151], v[4:5], off offset:64
	global_load_dwordx4 v[144:147], v[4:5], off offset:96
	global_load_dwordx4 v[140:143], v[4:5], off offset:128
	global_load_dwordx4 v[136:139], v[4:5], off offset:160
	global_load_dwordx4 v[132:135], v[4:5], off offset:192
	global_load_dwordx4 v[128:131], v[4:5], off offset:224
	v_mfma_f32_32x32x16_bf16 v[0:15], v[124:127], v[0:3], 0
	s_waitcnt vmcnt(12)
	v_mfma_f32_32x32x16_bf16 v[16:31], v[96:99], v[52:55], v[16:31]
	v_mfma_f32_32x32x16_bf16 v[0:15], v[120:123], v[52:55], v[0:15]
	s_waitcnt vmcnt(11)
	v_mfma_f32_32x32x16_bf16 v[16:31], v[92:95], v[48:51], v[16:31]
	v_mfma_f32_32x32x16_bf16 v[0:15], v[116:119], v[48:51], v[0:15]
	s_waitcnt vmcnt(10)
	v_mfma_f32_32x32x16_bf16 v[16:31], v[88:91], v[44:47], v[16:31]
	v_mfma_f32_32x32x16_bf16 v[0:15], v[112:115], v[44:47], v[0:15]
	s_waitcnt vmcnt(9)
	v_and_b32_e32 v44, 0xffff0000, v40
	v_cndmask_b32_e64 v40, v40, v44, s[52:53]
	v_and_b32_e32 v44, 0xffff, v40
	v_cndmask_b32_e64 v40, v40, v44, s[20:21]
	v_readlane_b32 s20, v254, 57
	v_and_b32_e32 v44, 0xffff0000, v41
	v_readlane_b32 s21, v254, 58
	s_waitcnt vmcnt(7)
	v_mfma_f32_32x32x16_bf16 v[48:63], v[100:103], v[32:35], 0
	v_cndmask_b32_e64 v41, v41, v44, s[20:21]
	v_readlane_b32 s20, v254, 55
	v_and_b32_e32 v44, 0xffff, v41
	v_readlane_b32 s21, v254, 56
	s_nop 1
	v_cndmask_b32_e64 v41, v41, v44, s[20:21]
	v_readlane_b32 s20, v254, 53
	v_and_b32_e32 v44, 0xffff0000, v42
	v_readlane_b32 s21, v254, 54
	s_waitcnt vmcnt(6)
	v_mfma_f32_32x32x16_bf16 v[48:63], v[96:99], v[152:155], v[48:63]
	v_cndmask_b32_e64 v42, v42, v44, s[20:21]
	v_readlane_b32 s20, v254, 51
	v_and_b32_e32 v44, 0xffff, v42
	v_readlane_b32 s21, v254, 52
	s_nop 1
	v_cndmask_b32_e64 v42, v42, v44, s[20:21]
	v_readlane_b32 s20, v254, 49
	v_and_b32_e32 v44, 0xffff0000, v43
	v_readlane_b32 s21, v254, 50
	s_waitcnt vmcnt(5)
	v_mfma_f32_32x32x16_bf16 v[48:63], v[92:95], v[148:151], v[48:63]
	v_mov_b32_e32 v93, s15
	v_cndmask_b32_e64 v43, v43, v44, s[20:21]
	v_readlane_b32 s20, v254, 47
	v_and_b32_e32 v44, 0xffff, v43
	v_readlane_b32 s21, v254, 48
	v_or_b32_e32 v92, s14, v162
	s_nop 0
	v_cndmask_b32_e64 v43, v43, v44, s[20:21]
	v_readlane_b32 s20, v255, 11
	v_readlane_b32 s21, v255, 12
	v_mfma_f32_32x32x16_bf16 v[16:31], v[84:87], v[40:43], v[16:31]
	v_mfma_f32_32x32x16_bf16 v[0:15], v[108:111], v[40:43], v[0:15]
	v_and_b32_e32 v40, 0xffff0000, v36
	v_cndmask_b32_e64 v36, v36, v40, s[20:21]
	v_readlane_b32 s20, v255, 9
	v_and_b32_e32 v40, 0xffff, v36
	v_readlane_b32 s21, v255, 10
	s_nop 1
	v_cndmask_b32_e64 v36, v36, v40, s[20:21]
	v_readlane_b32 s20, v255, 7
	v_and_b32_e32 v40, 0xffff0000, v37
	v_readlane_b32 s21, v255, 8
	s_waitcnt vmcnt(4)
	v_mfma_f32_32x32x16_bf16 v[48:63], v[88:91], v[144:147], v[48:63]
	v_mov_b32_e32 v89, s15
	v_cndmask_b32_e64 v37, v37, v40, s[20:21]
	v_readlane_b32 s20, v255, 5
	v_and_b32_e32 v40, 0xffff, v37
	v_readlane_b32 s21, v255, 6
	v_or_b32_e32 v88, s14, v178
	s_nop 0
	v_cndmask_b32_e64 v37, v37, v40, s[20:21]
	v_readlane_b32 s20, v255, 3
	v_and_b32_e32 v40, 0xffff0000, v38
	v_readlane_b32 s21, v255, 4
	s_waitcnt vmcnt(3)
	v_mfma_f32_32x32x16_bf16 v[48:63], v[84:87], v[140:143], v[48:63]
	v_mov_b32_e32 v85, s15
	v_cndmask_b32_e64 v38, v38, v40, s[20:21]
	v_readlane_b32 s20, v255, 1
	v_and_b32_e32 v40, 0xffff, v38
	v_readlane_b32 s21, v255, 2
	s_nop 1
	v_cndmask_b32_e64 v38, v38, v40, s[20:21]
	v_readlane_b32 s20, v254, 63
	v_and_b32_e32 v40, 0xffff0000, v39
	v_readlane_b32 s21, v255, 0
	s_waitcnt vmcnt(2)
	v_mfma_f32_32x32x16_bf16 v[48:63], v[80:83], v[136:139], v[48:63]
	v_cndmask_b32_e64 v39, v39, v40, s[20:21]
	v_readlane_b32 s20, v254, 61
	v_and_b32_e32 v40, 0xffff, v39
	v_readlane_b32 s21, v254, 62
	s_nop 1
	v_cndmask_b32_e64 v39, v39, v40, s[20:21]
	v_readlane_b32 s20, v255, 27
	v_readlane_b32 s21, v255, 28
	v_mfma_f32_32x32x16_bf16 v[16:31], v[80:83], v[36:39], v[16:31]
	s_waitcnt vmcnt(1)
	v_and_b32_e32 v80, 0xffff0000, v132
	v_cndmask_b32_e64 v80, v132, v80, s[20:21]
	v_readlane_b32 s20, v255, 25
	v_and_b32_e32 v81, 0xffff, v80
	v_readlane_b32 s21, v255, 26
	v_mfma_f32_32x32x16_bf16 v[0:15], v[104:107], v[36:39], v[0:15]
	s_nop 0
	v_cndmask_b32_e64 v80, v80, v81, s[20:21]
	v_readlane_b32 s20, v255, 23
	v_and_b32_e32 v81, 0xffff0000, v133
	v_readlane_b32 s21, v255, 24
	s_nop 1
	v_cndmask_b32_e64 v81, v133, v81, s[20:21]
	v_mfma_f32_32x32x16_bf16 v[32:47], v[124:127], v[32:35], 0
	v_readlane_b32 s20, v255, 21
	v_and_b32_e32 v82, 0xffff, v81
	v_readlane_b32 s21, v255, 22
	s_nop 1
	v_cndmask_b32_e64 v81, v81, v82, s[20:21]
	v_readlane_b32 s20, v255, 19
	v_mfma_f32_32x32x16_bf16 v[32:47], v[120:123], v[152:155], v[32:47]
	v_and_b32_e32 v82, 0xffff0000, v134
	v_readlane_b32 s21, v255, 20
	s_nop 1
	v_cndmask_b32_e64 v82, v134, v82, s[20:21]
	v_readlane_b32 s20, v255, 17
	v_and_b32_e32 v83, 0xffff, v82
	v_mfma_f32_32x32x16_bf16 v[32:47], v[116:119], v[148:151], v[32:47]
	v_readlane_b32 s21, v255, 18
	s_nop 1
	v_cndmask_b32_e64 v82, v82, v83, s[20:21]
	v_readlane_b32 s20, v255, 15
	v_and_b32_e32 v83, 0xffff0000, v135
	v_readlane_b32 s21, v255, 16
	v_mfma_f32_32x32x16_bf16 v[32:47], v[112:115], v[144:147], v[32:47]
	s_nop 0
	v_cndmask_b32_e64 v83, v135, v83, s[20:21]
	v_readlane_b32 s20, v255, 13
	v_and_b32_e32 v84, 0xffff, v83
	v_readlane_b32 s21, v255, 14
	v_mfma_f32_32x32x16_bf16 v[32:47], v[108:111], v[140:143], v[32:47]
	s_nop 0
	v_cndmask_b32_e64 v83, v83, v84, s[20:21]
	v_readlane_b32 s20, v255, 33
	v_readlane_b32 s21, v255, 34
	v_or_b32_e32 v84, s14, v180
	v_mfma_f32_32x32x16_bf16 v[32:47], v[104:107], v[136:139], v[32:47]
	v_mfma_f32_32x32x16_bf16 v[48:63], v[72:75], v[80:83], v[48:63]
	s_waitcnt vmcnt(0)
	v_and_b32_e32 v72, 0xffff0000, v128
	v_cndmask_b32_e64 v72, v128, v72, s[10:11]
	v_and_b32_e32 v73, 0xffff, v72
	v_cndmask_b32_e64 v72, v72, v73, s[8:9]
	v_and_b32_e32 v73, 0xffff0000, v129
	v_cndmask_b32_e64 v73, v129, v73, s[6:7]
	v_and_b32_e32 v74, 0xffff, v73
	v_mfma_f32_32x32x16_bf16 v[32:47], v[76:79], v[80:83], v[32:47]
	v_cndmask_b32_e64 v73, v73, v74, s[40:41]
	v_and_b32_e32 v74, 0xffff0000, v130
	v_cndmask_b32_e64 v74, v130, v74, s[2:3]
	v_and_b32_e32 v75, 0xffff, v74
	v_cndmask_b32_e64 v74, v74, v75, s[20:21]
	v_readlane_b32 s20, v255, 31
	v_and_b32_e32 v75, 0xffff0000, v131
	v_readlane_b32 s21, v255, 32
	v_mov_b32_e32 v81, s15
	v_or_b32_e32 v80, s14, v182
	v_cndmask_b32_e64 v75, v131, v75, s[20:21]
	v_readlane_b32 s20, v255, 29
	v_and_b32_e32 v76, 0xffff, v75
	v_readlane_b32 s21, v255, 30
	s_nop 1
	v_cndmask_b32_e64 v75, v75, v76, s[20:21]
	s_nop 1
	v_mfma_f32_32x32x16_bf16 v[48:63], v[64:67], v[72:75], v[48:63]
	v_mov_b32_e32 v67, s15
	v_or_b32_e32 v66, s14, v188
	v_mov_b32_e32 v65, s15
	v_or_b32_e32 v64, s14, v190
	v_mfma_f32_32x32x16_bf16 v[32:47], v[68:71], v[72:75], v[32:47]
	ds_write_b128 v175, v[16:19]
	ds_write_b128 v175, v[20:23] offset:16
	ds_write_b128 v175, v[24:27] offset:32
	ds_write_b128 v175, v[28:31] offset:48
	ds_write_b128 v175, v[0:3] offset:128
	ds_write_b128 v175, v[4:7] offset:144
	ds_write_b128 v175, v[8:11] offset:160
	ds_write_b128 v175, v[12:15] offset:176
	ds_write_b128 v177, v[48:51]
	ds_write_b128 v177, v[52:55] offset:16
	ds_write_b128 v177, v[56:59] offset:32
	ds_write_b128 v177, v[60:63] offset:48
	ds_write_b128 v177, v[32:35] offset:128
	ds_write_b128 v177, v[36:39] offset:144
	ds_write_b128 v177, v[40:43] offset:160
	ds_write_b128 v177, v[44:47] offset:176
	v_lshlrev_b64 v[0:1], 11, v[92:93]
	v_lshl_add_u64 v[2:3], v[206:207], 0, v[0:1]
	v_lshl_add_u64 v[0:1], v[204:205], 0, v[0:1]
	global_load_dwordx4 v[60:63], v[2:3], off nt
	global_load_dwordx4 v[56:59], v[0:1], off nt
	global_load_dword v94, v179, s[12:13] offset:256
	v_lshlrev_b64 v[0:1], 11, v[88:89]
	v_lshl_add_u64 v[2:3], v[206:207], 0, v[0:1]
	v_lshl_add_u64 v[0:1], v[204:205], 0, v[0:1]
	global_load_dwordx4 v[52:55], v[2:3], off nt
	global_load_dwordx4 v[48:51], v[0:1], off nt
	global_load_dword v90, v179, s[12:13] offset:288
	v_lshlrev_b64 v[0:1], 11, v[84:85]
	v_lshl_add_u64 v[2:3], v[206:207], 0, v[0:1]
	v_lshl_add_u64 v[0:1], v[204:205], 0, v[0:1]
	global_load_dwordx4 v[44:47], v[2:3], off nt
	global_load_dwordx4 v[40:43], v[0:1], off nt
	global_load_dword v86, v179, s[12:13] offset:320
	v_lshlrev_b64 v[0:1], 11, v[80:81]
	v_lshl_add_u64 v[2:3], v[206:207], 0, v[0:1]
	v_lshl_add_u64 v[0:1], v[204:205], 0, v[0:1]
	v_mov_b32_e32 v75, s15
	v_or_b32_e32 v74, s14, v184
	global_load_dwordx4 v[36:39], v[2:3], off nt
	global_load_dwordx4 v[32:35], v[0:1], off nt
	global_load_dword v82, v179, s[12:13] offset:352
	v_lshlrev_b64 v[0:1], 11, v[74:75]
	v_lshl_add_u64 v[2:3], v[206:207], 0, v[0:1]
	v_lshl_add_u64 v[0:1], v[204:205], 0, v[0:1]
	v_mov_b32_e32 v71, s15
	v_or_b32_e32 v70, s14, v186
	global_load_dwordx4 v[24:27], v[2:3], off nt
	global_load_dwordx4 v[20:23], v[0:1], off nt
	global_load_dword v76, v179, s[12:13] offset:384
	v_lshlrev_b64 v[0:1], 11, v[70:71]
	v_lshl_add_u64 v[2:3], v[206:207], 0, v[0:1]
	v_lshl_add_u64 v[0:1], v[204:205], 0, v[0:1]
	global_load_dwordx4 v[16:19], v[2:3], off nt
	global_load_dwordx4 v[12:15], v[0:1], off nt
	global_load_dword v72, v179, s[12:13] offset:416
	v_lshlrev_b64 v[0:1], 11, v[66:67]
	v_lshlrev_b64 v[28:29], 11, v[64:65]
	v_lshl_add_u64 v[2:3], v[206:207], 0, v[0:1]
	v_lshl_add_u64 v[0:1], v[204:205], 0, v[0:1]
	v_lshl_add_u64 v[8:9], v[206:207], 0, v[28:29]
	v_lshl_add_u64 v[28:29], v[204:205], 0, v[28:29]
	global_load_dwordx4 v[4:7], v[2:3], off nt
	s_nop 0
	global_load_dwordx4 v[0:3], v[0:1], off nt
	s_nop 0
	global_load_dword v68, v179, s[12:13] offset:448
	s_nop 0
	global_load_dwordx4 v[8:11], v[8:9], off nt
	s_nop 0
	global_load_dwordx4 v[28:31], v[28:29], off nt
	s_nop 0
	global_load_dword v78, v179, s[12:13] offset:480
	s_waitcnt vmcnt(1)
	ds_read_b128 v[96:99], v173
	ds_read_b128 v[100:103], v173 offset:16
	v_lshlrev_b32_e32 v104, 16, v60
	v_and_b32_e32 v105, 0xffff0000, v60
	v_lshlrev_b32_e32 v60, 16, v61
	s_waitcnt lgkmcnt(1)
	v_pk_add_f32 v[96:97], v[94:95], v[96:97] op_sel_hi:[0,1]
	v_pk_mul_f32 v[96:97], v[96:97], v[104:105]
	v_lshlrev_b32_e32 v104, 16, v56
	v_and_b32_e32 v105, 0xffff0000, v56
	v_pk_mul_f32 v[96:97], v[96:97], v[104:105]
	v_and_b32_e32 v61, 0xffff0000, v61
	v_cvt_pk_bf16_f32 v56, v96, v97
	v_pk_add_f32 v[96:97], v[94:95], v[98:99] op_sel_hi:[0,1]
	v_pk_mul_f32 v[60:61], v[96:97], v[60:61]
	v_lshlrev_b32_e32 v96, 16, v57
	v_and_b32_e32 v97, 0xffff0000, v57
	v_pk_mul_f32 v[60:61], v[60:61], v[96:97]
	s_waitcnt lgkmcnt(0)
	v_pk_add_f32 v[96:97], v[94:95], v[100:101] op_sel_hi:[0,1]
	v_cvt_pk_bf16_f32 v57, v60, v61
	v_lshlrev_b32_e32 v60, 16, v62
	v_and_b32_e32 v61, 0xffff0000, v62
	v_pk_mul_f32 v[60:61], v[96:97], v[60:61]
	v_lshlrev_b32_e32 v96, 16, v58
	v_and_b32_e32 v97, 0xffff0000, v58
	v_pk_mul_f32 v[60:61], v[60:61], v[96:97]
	s_nop 0
	v_cvt_pk_bf16_f32 v58, v60, v61
	v_lshlrev_b32_e32 v60, 16, v63
	v_and_b32_e32 v61, 0xffff0000, v63
	v_pk_add_f32 v[62:63], v[94:95], v[102:103] op_sel_hi:[0,1]
	v_pk_mul_f32 v[60:61], v[62:63], v[60:61]
	v_lshlrev_b32_e32 v62, 16, v59
	v_and_b32_e32 v63, 0xffff0000, v59
	v_pk_mul_f32 v[60:61], v[60:61], v[62:63]
	s_nop 0
	v_cvt_pk_bf16_f32 v59, v60, v61
	v_lshlrev_b64 v[60:61], 12, v[92:93]
	v_lshl_add_u64 v[60:61], v[202:203], 0, v[60:61]
	global_store_dwordx4 v[60:61], v[56:59], off
	ds_read_b128 v[56:59], v173 offset:2176
	ds_read_b128 v[60:63], v173 offset:2192
	v_lshlrev_b32_e32 v92, 16, v52
	v_and_b32_e32 v93, 0xffff0000, v52
	v_lshlrev_b32_e32 v52, 16, v53
	s_waitcnt lgkmcnt(1)
	v_pk_add_f32 v[56:57], v[90:91], v[56:57] op_sel_hi:[0,1]
	v_pk_mul_f32 v[56:57], v[56:57], v[92:93]
	v_lshlrev_b32_e32 v92, 16, v48
	v_and_b32_e32 v93, 0xffff0000, v48
	v_pk_mul_f32 v[56:57], v[56:57], v[92:93]
	v_and_b32_e32 v53, 0xffff0000, v53
	v_cvt_pk_bf16_f32 v48, v56, v57
	v_pk_add_f32 v[56:57], v[90:91], v[58:59] op_sel_hi:[0,1]
	v_pk_mul_f32 v[52:53], v[56:57], v[52:53]
	v_lshlrev_b32_e32 v56, 16, v49
	v_and_b32_e32 v57, 0xffff0000, v49
	v_pk_mul_f32 v[52:53], v[52:53], v[56:57]
	s_waitcnt lgkmcnt(0)
	v_pk_add_f32 v[56:57], v[90:91], v[60:61] op_sel_hi:[0,1]
	v_cvt_pk_bf16_f32 v49, v52, v53
	v_lshlrev_b32_e32 v52, 16, v54
	v_and_b32_e32 v53, 0xffff0000, v54
	v_pk_mul_f32 v[52:53], v[56:57], v[52:53]
	v_lshlrev_b32_e32 v56, 16, v50
	v_and_b32_e32 v57, 0xffff0000, v50
	v_pk_mul_f32 v[52:53], v[52:53], v[56:57]
	v_lshlrev_b32_e32 v56, 16, v44
	v_cvt_pk_bf16_f32 v50, v52, v53
	v_lshlrev_b32_e32 v52, 16, v55
	v_and_b32_e32 v53, 0xffff0000, v55
	v_pk_add_f32 v[54:55], v[90:91], v[62:63] op_sel_hi:[0,1]
	v_pk_mul_f32 v[52:53], v[54:55], v[52:53]
	v_lshlrev_b32_e32 v54, 16, v51
	v_and_b32_e32 v55, 0xffff0000, v51
	v_pk_mul_f32 v[52:53], v[52:53], v[54:55]
	v_and_b32_e32 v57, 0xffff0000, v44
	v_cvt_pk_bf16_f32 v51, v52, v53
	v_lshlrev_b64 v[52:53], 12, v[88:89]
	v_lshl_add_u64 v[52:53], v[202:203], 0, v[52:53]
	global_store_dwordx4 v[52:53], v[48:51], off
	ds_read_b128 v[48:51], v173 offset:4352
	ds_read_b128 v[52:55], v173 offset:4368
	v_lshlrev_b32_e32 v44, 16, v45
	v_and_b32_e32 v45, 0xffff0000, v45
	s_waitcnt lgkmcnt(1)
	v_pk_add_f32 v[48:49], v[86:87], v[48:49] op_sel_hi:[0,1]
	v_pk_mul_f32 v[48:49], v[48:49], v[56:57]
	v_lshlrev_b32_e32 v56, 16, v40
	v_and_b32_e32 v57, 0xffff0000, v40
	v_pk_mul_f32 v[48:49], v[48:49], v[56:57]
	s_nop 0
	v_cvt_pk_bf16_f32 v40, v48, v49
	v_pk_add_f32 v[48:49], v[86:87], v[50:51] op_sel_hi:[0,1]
	v_pk_mul_f32 v[44:45], v[48:49], v[44:45]
	v_lshlrev_b32_e32 v48, 16, v41
	v_and_b32_e32 v49, 0xffff0000, v41
	v_pk_mul_f32 v[44:45], v[44:45], v[48:49]
	s_waitcnt lgkmcnt(0)
	v_pk_add_f32 v[48:49], v[86:87], v[52:53] op_sel_hi:[0,1]
	v_cvt_pk_bf16_f32 v41, v44, v45
	v_lshlrev_b32_e32 v44, 16, v46
	v_and_b32_e32 v45, 0xffff0000, v46
	v_pk_mul_f32 v[44:45], v[48:49], v[44:45]
	v_lshlrev_b32_e32 v48, 16, v42
	v_and_b32_e32 v49, 0xffff0000, v42
	v_pk_mul_f32 v[44:45], v[44:45], v[48:49]
	v_lshlrev_b32_e32 v48, 16, v36
	v_cvt_pk_bf16_f32 v42, v44, v45
	v_lshlrev_b32_e32 v44, 16, v47
	v_and_b32_e32 v45, 0xffff0000, v47
	v_pk_add_f32 v[46:47], v[86:87], v[54:55] op_sel_hi:[0,1]
	v_pk_mul_f32 v[44:45], v[46:47], v[44:45]
	v_lshlrev_b32_e32 v46, 16, v43
	v_and_b32_e32 v47, 0xffff0000, v43
	v_pk_mul_f32 v[44:45], v[44:45], v[46:47]
	v_and_b32_e32 v49, 0xffff0000, v36
	v_cvt_pk_bf16_f32 v43, v44, v45
	v_lshlrev_b64 v[44:45], 12, v[84:85]
	v_lshl_add_u64 v[44:45], v[202:203], 0, v[44:45]
	global_store_dwordx4 v[44:45], v[40:43], off
	ds_read_b128 v[40:43], v173 offset:6528
	ds_read_b128 v[44:47], v173 offset:6544
	v_lshlrev_b32_e32 v36, 16, v37
	v_and_b32_e32 v37, 0xffff0000, v37
	s_waitcnt lgkmcnt(1)
	v_pk_add_f32 v[40:41], v[82:83], v[40:41] op_sel_hi:[0,1]
	v_pk_mul_f32 v[40:41], v[40:41], v[48:49]
	v_lshlrev_b32_e32 v48, 16, v32
	v_and_b32_e32 v49, 0xffff0000, v32
	v_pk_mul_f32 v[40:41], v[40:41], v[48:49]
	s_nop 0
	v_cvt_pk_bf16_f32 v32, v40, v41
	v_pk_add_f32 v[40:41], v[82:83], v[42:43] op_sel_hi:[0,1]
	v_pk_mul_f32 v[36:37], v[40:41], v[36:37]
	v_lshlrev_b32_e32 v40, 16, v33
	v_and_b32_e32 v41, 0xffff0000, v33
	v_pk_mul_f32 v[36:37], v[36:37], v[40:41]
	s_waitcnt lgkmcnt(0)
	v_pk_add_f32 v[40:41], v[82:83], v[44:45] op_sel_hi:[0,1]
	v_cvt_pk_bf16_f32 v33, v36, v37
	v_lshlrev_b32_e32 v36, 16, v38
	v_and_b32_e32 v37, 0xffff0000, v38
	v_pk_mul_f32 v[36:37], v[40:41], v[36:37]
	v_lshlrev_b32_e32 v40, 16, v34
	v_and_b32_e32 v41, 0xffff0000, v34
	v_pk_mul_f32 v[36:37], v[36:37], v[40:41]
	v_lshlrev_b32_e32 v40, 16, v24
	v_cvt_pk_bf16_f32 v34, v36, v37
	v_lshlrev_b32_e32 v36, 16, v39
	v_and_b32_e32 v37, 0xffff0000, v39
	v_pk_add_f32 v[38:39], v[82:83], v[46:47] op_sel_hi:[0,1]
	v_pk_mul_f32 v[36:37], v[38:39], v[36:37]
	v_lshlrev_b32_e32 v38, 16, v35
	v_and_b32_e32 v39, 0xffff0000, v35
	v_pk_mul_f32 v[36:37], v[36:37], v[38:39]
	v_and_b32_e32 v41, 0xffff0000, v24
	v_cvt_pk_bf16_f32 v35, v36, v37
	v_lshlrev_b64 v[36:37], 12, v[80:81]
	v_lshl_add_u64 v[36:37], v[202:203], 0, v[36:37]
	global_store_dwordx4 v[36:37], v[32:35], off
	ds_read_b128 v[36:39], v173 offset:8704
	ds_read_b128 v[32:35], v173 offset:8720
	v_lshlrev_b32_e32 v24, 16, v25
	v_and_b32_e32 v25, 0xffff0000, v25
	s_waitcnt lgkmcnt(1)
	v_pk_add_f32 v[36:37], v[76:77], v[36:37] op_sel_hi:[0,1]
	v_pk_mul_f32 v[36:37], v[36:37], v[40:41]
	v_lshlrev_b32_e32 v40, 16, v20
	v_and_b32_e32 v41, 0xffff0000, v20
	v_pk_mul_f32 v[36:37], v[36:37], v[40:41]
	s_waitcnt lgkmcnt(0)
	v_pk_add_f32 v[32:33], v[76:77], v[32:33] op_sel_hi:[0,1]
	v_cvt_pk_bf16_f32 v20, v36, v37
	v_pk_add_f32 v[36:37], v[76:77], v[38:39] op_sel_hi:[0,1]
	v_pk_mul_f32 v[24:25], v[36:37], v[24:25]
	v_lshlrev_b32_e32 v36, 16, v21
	v_and_b32_e32 v37, 0xffff0000, v21
	v_pk_mul_f32 v[24:25], v[24:25], v[36:37]
	s_nop 0
	v_cvt_pk_bf16_f32 v21, v24, v25
	v_lshlrev_b32_e32 v24, 16, v26
	v_and_b32_e32 v25, 0xffff0000, v26
	v_pk_mul_f32 v[24:25], v[32:33], v[24:25]
	v_lshlrev_b32_e32 v32, 16, v22
	v_and_b32_e32 v33, 0xffff0000, v22
	v_pk_mul_f32 v[24:25], v[24:25], v[32:33]
	v_lshlrev_b32_e32 v32, 16, v16
	v_cvt_pk_bf16_f32 v22, v24, v25
	v_lshlrev_b32_e32 v24, 16, v27
	v_and_b32_e32 v25, 0xffff0000, v27
	v_pk_add_f32 v[26:27], v[76:77], v[34:35] op_sel_hi:[0,1]
	v_pk_mul_f32 v[24:25], v[26:27], v[24:25]
	v_lshlrev_b32_e32 v26, 16, v23
	v_and_b32_e32 v27, 0xffff0000, v23
	v_pk_mul_f32 v[24:25], v[24:25], v[26:27]
	v_and_b32_e32 v33, 0xffff0000, v16
	v_cvt_pk_bf16_f32 v23, v24, v25
	v_lshlrev_b64 v[24:25], 12, v[74:75]
	v_lshl_add_u64 v[24:25], v[202:203], 0, v[24:25]
	global_store_dwordx4 v[24:25], v[20:23], off
	ds_read_b128 v[20:23], v173 offset:10880
	ds_read_b128 v[24:27], v173 offset:10896
	v_lshlrev_b32_e32 v16, 16, v17
	v_and_b32_e32 v17, 0xffff0000, v17
	s_waitcnt lgkmcnt(1)
	v_pk_add_f32 v[20:21], v[72:73], v[20:21] op_sel_hi:[0,1]
	v_pk_mul_f32 v[20:21], v[20:21], v[32:33]
	v_lshlrev_b32_e32 v32, 16, v12
	v_and_b32_e32 v33, 0xffff0000, v12
	v_pk_mul_f32 v[20:21], v[20:21], v[32:33]
	s_nop 0
	v_cvt_pk_bf16_f32 v12, v20, v21
	v_pk_add_f32 v[20:21], v[72:73], v[22:23] op_sel_hi:[0,1]
	v_pk_mul_f32 v[16:17], v[20:21], v[16:17]
	v_lshlrev_b32_e32 v20, 16, v13
	v_and_b32_e32 v21, 0xffff0000, v13
	v_pk_mul_f32 v[16:17], v[16:17], v[20:21]
	s_waitcnt lgkmcnt(0)
	v_pk_add_f32 v[20:21], v[72:73], v[24:25] op_sel_hi:[0,1]
	v_cvt_pk_bf16_f32 v13, v16, v17
	v_lshlrev_b32_e32 v16, 16, v18
	v_and_b32_e32 v17, 0xffff0000, v18
	v_pk_mul_f32 v[16:17], v[20:21], v[16:17]
	v_lshlrev_b32_e32 v20, 16, v14
	v_and_b32_e32 v21, 0xffff0000, v14
	v_pk_mul_f32 v[16:17], v[16:17], v[20:21]
	v_lshlrev_b32_e32 v20, 16, v4
	v_cvt_pk_bf16_f32 v14, v16, v17
	v_lshlrev_b32_e32 v16, 16, v19
	v_and_b32_e32 v17, 0xffff0000, v19
	v_pk_add_f32 v[18:19], v[72:73], v[26:27] op_sel_hi:[0,1]
	v_pk_mul_f32 v[16:17], v[18:19], v[16:17]
	v_lshlrev_b32_e32 v18, 16, v15
	v_and_b32_e32 v19, 0xffff0000, v15
	v_pk_mul_f32 v[16:17], v[16:17], v[18:19]
	v_and_b32_e32 v21, 0xffff0000, v4
	v_cvt_pk_bf16_f32 v15, v16, v17
	v_lshlrev_b64 v[16:17], 12, v[70:71]
	v_lshl_add_u64 v[16:17], v[202:203], 0, v[16:17]
	global_store_dwordx4 v[16:17], v[12:15], off
	ds_read_b128 v[12:15], v173 offset:13056
	ds_read_b128 v[16:19], v173 offset:13072
	v_lshlrev_b32_e32 v4, 16, v5
	v_and_b32_e32 v5, 0xffff0000, v5
	s_waitcnt lgkmcnt(1)
	v_pk_add_f32 v[12:13], v[68:69], v[12:13] op_sel_hi:[0,1]
	v_pk_mul_f32 v[12:13], v[12:13], v[20:21]
	v_lshlrev_b32_e32 v20, 16, v0
	v_and_b32_e32 v21, 0xffff0000, v0
	v_pk_mul_f32 v[12:13], v[12:13], v[20:21]
	s_nop 0
	v_cvt_pk_bf16_f32 v0, v12, v13
	v_pk_add_f32 v[12:13], v[68:69], v[14:15] op_sel_hi:[0,1]
	v_pk_mul_f32 v[4:5], v[12:13], v[4:5]
	v_lshlrev_b32_e32 v12, 16, v1
	v_and_b32_e32 v13, 0xffff0000, v1
	v_pk_mul_f32 v[4:5], v[4:5], v[12:13]
	s_waitcnt lgkmcnt(0)
	v_pk_add_f32 v[12:13], v[68:69], v[16:17] op_sel_hi:[0,1]
	v_cvt_pk_bf16_f32 v1, v4, v5
	v_lshlrev_b32_e32 v4, 16, v6
	v_and_b32_e32 v5, 0xffff0000, v6
	v_pk_mul_f32 v[4:5], v[12:13], v[4:5]
	v_lshlrev_b32_e32 v12, 16, v2
	v_and_b32_e32 v13, 0xffff0000, v2
	v_pk_mul_f32 v[4:5], v[4:5], v[12:13]
	v_lshlrev_b32_e32 v12, 16, v8
	v_cvt_pk_bf16_f32 v2, v4, v5
	v_lshlrev_b32_e32 v4, 16, v7
	v_and_b32_e32 v5, 0xffff0000, v7
	v_pk_add_f32 v[6:7], v[68:69], v[18:19] op_sel_hi:[0,1]
	v_pk_mul_f32 v[4:5], v[6:7], v[4:5]
	v_lshlrev_b32_e32 v6, 16, v3
	v_and_b32_e32 v7, 0xffff0000, v3
	v_pk_mul_f32 v[4:5], v[4:5], v[6:7]
	v_and_b32_e32 v13, 0xffff0000, v8
	v_cvt_pk_bf16_f32 v3, v4, v5
	v_lshlrev_b64 v[4:5], 12, v[66:67]
	v_lshl_add_u64 v[4:5], v[202:203], 0, v[4:5]
	global_store_dwordx4 v[4:5], v[0:3], off
	ds_read_b128 v[0:3], v173 offset:15232
	ds_read_b128 v[4:7], v173 offset:15248
	v_lshlrev_b32_e32 v8, 16, v9
	v_and_b32_e32 v9, 0xffff0000, v9
	s_waitcnt vmcnt(7) lgkmcnt(1)
	v_pk_add_f32 v[0:1], v[78:79], v[0:1] op_sel_hi:[0,1]
	v_pk_add_f32 v[2:3], v[78:79], v[2:3] op_sel_hi:[0,1]
	v_pk_mul_f32 v[0:1], v[0:1], v[12:13]
	v_lshlrev_b32_e32 v12, 16, v28
	v_and_b32_e32 v13, 0xffff0000, v28
	v_pk_mul_f32 v[2:3], v[2:3], v[8:9]
	v_lshlrev_b32_e32 v8, 16, v29
	v_and_b32_e32 v9, 0xffff0000, v29
	v_pk_mul_f32 v[0:1], v[0:1], v[12:13]
	v_pk_mul_f32 v[2:3], v[2:3], v[8:9]
	v_cvt_pk_bf16_f32 v0, v0, v1
	v_cvt_pk_bf16_f32 v1, v2, v3
	v_lshlrev_b32_e32 v2, 16, v10
	v_and_b32_e32 v3, 0xffff0000, v10
	s_waitcnt lgkmcnt(0)
	v_pk_add_f32 v[4:5], v[78:79], v[4:5] op_sel_hi:[0,1]
	v_pk_mul_f32 v[2:3], v[4:5], v[2:3]
	v_lshlrev_b32_e32 v4, 16, v30
	v_and_b32_e32 v5, 0xffff0000, v30
	v_pk_mul_f32 v[2:3], v[2:3], v[4:5]
	v_lshlrev_b32_e32 v4, 16, v11
	v_and_b32_e32 v5, 0xffff0000, v11
	v_pk_add_f32 v[6:7], v[78:79], v[6:7] op_sel_hi:[0,1]
	v_pk_mul_f32 v[4:5], v[6:7], v[4:5]
	v_lshlrev_b32_e32 v6, 16, v31
	v_and_b32_e32 v7, 0xffff0000, v31
	v_pk_mul_f32 v[4:5], v[4:5], v[6:7]
	v_cvt_pk_bf16_f32 v2, v2, v3
	v_cvt_pk_bf16_f32 v3, v4, v5
	v_lshlrev_b64 v[4:5], 12, v[64:65]
	v_lshl_add_u64 v[4:5], v[202:203], 0, v[4:5]
	global_store_dwordx4 v[4:5], v[0:3], off
	s_cbranch_scc1 .LBB0_124
	v_readlane_b32 s44, v253, 42
	v_readlane_b32 s29, v253, 41
	v_readlane_b32 s45, v253, 43
	v_readlane_b32 s37, v253, 46
	s_mov_b32 s46, s27
